# dilated-attention units: V tile loads also whole-row (all global accesses of the unit now touch full cache lines)
# baseline (speedup 1.0000x reference)
.LBB0_314:
	s_mov_b64 exec, -1
	s_load_dwordx2 s[100:101], s[0:1], 0xf0
	s_mov_b32 s98, s97
	v_and_b32_e32 v128, 31, v206
	v_bfe_u32 v249, v206, 5, 1
	v_lshlrev_b32_e32 v129, 4, v249
	v_lshlrev_b32_e32 v250, 2, v249
	v_sub_u32_e32 v130, v128, v250
	v_mov_b32_e32 v131, 0xf149f2ca
	v_and_b32_e32 v133, 7, v206
	v_lshlrev_b32_e32 v133, 4, v133
	v_and_b32_e32 v134, 15, v206
	v_lshlrev_b32_e32 v134, 4, v134
	v_lshrrev_b32_e32 v251, 6, v206
	v_lshlrev_b32_e32 v251, 14, v251
	v_and_b32_e32 v252, 7, v206
	v_mul_u32_u24_e32 v252, 0x240, v252
	v_bfe_u32 v200, v206, 3, 3
	v_lshl_add_u32 v200, v200, 1, v252
	v_add_u32_e32 v200, v200, v251
	v_mul_u32_u24_e32 v252, 72, v128
	v_lshl_add_u32 v201, v249, 3, v252
	v_add_u32_e32 v201, v201, v251
	v_bfe_u32 v252, v206, 3, 3
	v_mul_u32_u24_e32 v252, 144, v252
	v_add3_u32 v202, v252, v133, v251
	v_add_u32_e32 v202, 4608, v202
	v_mul_u32_u24_e32 v252, 144, v128
	v_add3_u32 v203, v252, v129, v251
	v_add_u32_e32 v203, 4608, v203
	v_bfe_u32 v252, v206, 4, 2
	v_mul_u32_u24_e32 v252, 272, v252
	v_add3_u32 v204, v252, v134, v251
	v_add_u32_e32 v204, 4608, v204
	v_mul_u32_u24_e32 v252, 272, v128
	v_add3_u32 v205, v252, v129, v251
	v_add_u32_e32 v205, 4608, v205
	s_waitcnt lgkmcnt(0)
.Ldil_p0L0_loop:
	s_and_b32 s4, s98, 127
	s_mov_b32 s5, 0
	s_lshr_b32 s6, s98, 10
	s_and_b32 s7, s98, 0x380
	s_lshl_b32 s99, s6, 12
	s_add_u32 s8, s99, s5
	s_sub_u32 s9, 4, s4
	s_max_i32 s9, s9, 0
	s_lshl_b32 s4, s4, 5
	v_add_u32_e32 v135, s4, v128
	s_lshl_b32 s99, s8, 10
	s_add_u32 s99, s99, s7
	s_add_u32 s64, s99, 0x16000000
	s_add_u32 s64, s100, s64
	s_addc_u32 s65, s101, 0
	s_add_u32 s72, s64, 0x2000000
	s_addc_u32 s73, s65, 0
	s_add_u32 s52, s72, 0x2000000
	s_addc_u32 s53, s73, 0
	s_mov_b64 s[80:81], s[52:53]
	s_add_u32 s82, s80, 0x2000
	s_addc_u32 s83, s81, 0
	s_add_u32 s84, s82, 0x2000
	s_addc_u32 s85, s83, 0
	s_add_u32 s86, s84, 0x2000
	s_addc_u32 s87, s85, 0
	s_add_u32 s66, s64, 0x2000
	s_addc_u32 s67, s65, 0
	s_add_u32 s74, s72, 0x2000
	s_addc_u32 s75, s73, 0
	s_add_u32 s68, s66, 0x2000
	s_addc_u32 s69, s67, 0
	s_add_u32 s76, s74, 0x2000
	s_addc_u32 s77, s75, 0
	s_add_u32 s70, s68, 0x2000
	s_addc_u32 s71, s69, 0
	s_add_u32 s78, s76, 0x2000
	s_addc_u32 s79, s77, 0
	v_bfe_u32 v249, v206, 3, 3
	v_add_u32_e32 v249, s4, v249
	v_mov_b32_e32 v253, v249
	v_lshl_add_u32 v250, v249, 10, v133
	global_load_dwordx4 v[152:155], v250, s[64:65]
	global_load_dwordx4 v[156:159], v250, s[66:67]
	global_load_dwordx4 v[160:163], v250, s[68:69]
	global_load_dwordx4 v[164:167], v250, s[70:71]
	s_max_u32 s99, s9, 0
	s_lshl_b32 s99, s99, 5
	s_addk_i32 s99, 0xff80
	v_add_u32_e32 v250, s99, v249
	v_lshl_add_u32 v250, v250, 10, v133
	global_load_dwordx4 v[0:3], v250, s[72:73]
	global_load_dwordx4 v[4:7], v250, s[74:75]
	global_load_dwordx4 v[8:11], v250, s[76:77]
	global_load_dwordx4 v[12:15], v250, s[78:79]
	s_max_u32 s99, s9, 1
	s_lshl_b32 s99, s99, 5
	s_addk_i32 s99, 0xff80
	v_add_u32_e32 v250, s99, v249
	v_lshl_add_u32 v250, v250, 10, v133
	global_load_dwordx4 v[16:19], v250, s[72:73]
	global_load_dwordx4 v[20:23], v250, s[74:75]
	global_load_dwordx4 v[24:27], v250, s[76:77]
	global_load_dwordx4 v[28:31], v250, s[78:79]
	s_max_u32 s99, s9, 2
	s_lshl_b32 s99, s99, 5
	s_addk_i32 s99, 0xff80
	v_add_u32_e32 v250, s99, v249
	v_lshl_add_u32 v250, v250, 10, v133
	global_load_dwordx4 v[32:35], v250, s[72:73]
	global_load_dwordx4 v[36:39], v250, s[74:75]
	global_load_dwordx4 v[40:43], v250, s[76:77]
	global_load_dwordx4 v[44:47], v250, s[78:79]
	s_max_u32 s99, s9, 3
	s_lshl_b32 s99, s99, 5
	s_addk_i32 s99, 0xff80
	v_add_u32_e32 v250, s99, v249
	v_lshl_add_u32 v250, v250, 10, v133
	global_load_dwordx4 v[48:51], v250, s[72:73]
	global_load_dwordx4 v[52:55], v250, s[74:75]
	global_load_dwordx4 v[56:59], v250, s[76:77]
	global_load_dwordx4 v[60:63], v250, s[78:79]
	s_max_u32 s99, s9, 4
	s_lshl_b32 s99, s99, 5
	s_addk_i32 s99, 0xff80
	v_add_u32_e32 v250, s99, v249
	v_lshl_add_u32 v250, v250, 10, v133
	global_load_dwordx4 v[64:67], v250, s[72:73]
	global_load_dwordx4 v[68:71], v250, s[74:75]
	global_load_dwordx4 v[72:75], v250, s[76:77]
	global_load_dwordx4 v[76:79], v250, s[78:79]
	s_lshl_b32 s99, s8, 5
	s_lshr_b32 s58, s7, 5
	s_add_u32 s99, s99, s58
	s_add_u32 s99, s99, 0x400000
	s_add_u32 s58, s100, s99
	s_addc_u32 s59, s101, 0
	s_add_u32 s60, s58, 0x100000
	s_addc_u32 s61, s59, 0
	v_lshlrev_b32_e32 v240, 5, v135
	s_lshl_b32 s99, s8, 11
	s_lshl_b32 s56, s7, 1
	s_add_u32 s99, s99, s56
	s_add_u32 s99, s99, 0x8000000
	s_add_u32 s56, s100, s99
	s_addc_u32 s57, s101, 0
	v_bfe_u32 v251, v206, 4, 2
	v_add_u32_e32 v251, s4, v251
	v_lshl_add_u32 v241, v251, 11, v134
	v_mov_b32_e32 v244, v131
	v_mov_b32_e32 v245, 0
	v_mov_b32_e32 v208, 0
	v_mov_b32_e32 v224, 0
	v_mov_b32_e32 v209, 0
	v_mov_b32_e32 v225, 0
	v_mov_b32_e32 v210, 0
	v_mov_b32_e32 v226, 0
	v_mov_b32_e32 v211, 0
	v_mov_b32_e32 v227, 0
	v_mov_b32_e32 v212, 0
	v_mov_b32_e32 v228, 0
	v_mov_b32_e32 v213, 0
	v_mov_b32_e32 v229, 0
	v_mov_b32_e32 v214, 0
	v_mov_b32_e32 v230, 0
	v_mov_b32_e32 v215, 0
	v_mov_b32_e32 v231, 0
	v_mov_b32_e32 v216, 0
	v_mov_b32_e32 v232, 0
	v_mov_b32_e32 v217, 0
	v_mov_b32_e32 v233, 0
	v_mov_b32_e32 v218, 0
	v_mov_b32_e32 v234, 0
	v_mov_b32_e32 v219, 0
	v_mov_b32_e32 v235, 0
	v_mov_b32_e32 v220, 0
	v_mov_b32_e32 v236, 0
	v_mov_b32_e32 v221, 0
	v_mov_b32_e32 v237, 0
	v_mov_b32_e32 v222, 0
	v_mov_b32_e32 v238, 0
	v_mov_b32_e32 v223, 0
	v_mov_b32_e32 v239, 0
	v_mov_b32_e32 v243, v131
	s_waitcnt vmcnt(20)
	ds_write_b128 v202, v[152:155]
	ds_write_b128 v202, v[156:159] offset:1152
	ds_write_b128 v202, v[160:163] offset:2304
	ds_write_b128 v202, v[164:167] offset:3456
	s_waitcnt lgkmcnt(0)
	ds_read_b128 v[136:139], v203
	ds_read_b128 v[140:143], v203 offset:32
	ds_read_b128 v[144:147], v203 offset:64
	ds_read_b128 v[148:151], v203 offset:96
	s_cmp_gt_u32 s9, 0
	s_cbranch_scc1 .Ldil_p0L0_kskip0
	s_waitcnt vmcnt(16)
	s_waitcnt lgkmcnt(0)
	ds_write_b128 v202, v[0:3]
	ds_write_b128 v202, v[4:7] offset:1152
	ds_write_b128 v202, v[8:11] offset:2304
	ds_write_b128 v202, v[12:15] offset:3456
	s_waitcnt lgkmcnt(0)
	s_max_u32 s99, s9, 0
	s_lshl_b32 s99, s99, 5
	s_addk_i32 s99, 0xff80
	v_add_u32_e32 v250, s99, v253
	v_lshl_add_u32 v250, v250, 10, v133
	global_load_dwordx4 v[0:3], v250, s[80:81]
	global_load_dwordx4 v[4:7], v250, s[82:83]
	global_load_dwordx4 v[8:11], v250, s[84:85]
	global_load_dwordx4 v[12:15], v250, s[86:87]
	ds_read_b128 v[152:155], v203
	ds_read_b128 v[156:159], v203 offset:32
	ds_read_b128 v[160:163], v203 offset:64
	ds_read_b128 v[164:167], v203 offset:96
	s_waitcnt lgkmcnt(0)
	v_mfma_f32_32x32x16_bf16 v[80:95], v[152:155], v[136:139], 0
	v_mfma_f32_32x32x16_bf16 v[80:95], v[156:159], v[140:143], v[80:95]
	v_mfma_f32_32x32x16_bf16 v[80:95], v[160:163], v[144:147], v[80:95]
	v_mfma_f32_32x32x16_bf16 v[80:95], v[164:167], v[148:151], v[80:95]
	s_nop 7
	s_nop 3
	v_cmp_gt_i32_e64 s[34:35], v130, 0
	v_cmp_gt_i32_e64 s[36:37], v130, 1
	v_cmp_gt_i32_e64 s[38:39], v130, 2
	v_cmp_gt_i32_e64 s[40:41], v130, 3
	v_cndmask_b32_e64 v80, v80, v131, s[34:35]
	v_cndmask_b32_e64 v81, v81, v131, s[36:37]
	v_cndmask_b32_e64 v82, v82, v131, s[38:39]
	v_cndmask_b32_e64 v83, v83, v131, s[40:41]
	v_cmp_gt_i32_e64 s[34:35], v130, 8
	v_cmp_gt_i32_e64 s[36:37], v130, 9
	v_cmp_gt_i32_e64 s[38:39], v130, 10
	v_cmp_gt_i32_e64 s[40:41], v130, 11
	v_cndmask_b32_e64 v84, v84, v131, s[34:35]
	v_cndmask_b32_e64 v85, v85, v131, s[36:37]
	v_cndmask_b32_e64 v86, v86, v131, s[38:39]
	v_cndmask_b32_e64 v87, v87, v131, s[40:41]
	v_cmp_gt_i32_e64 s[34:35], v130, 16
	v_cmp_gt_i32_e64 s[36:37], v130, 17
	v_cmp_gt_i32_e64 s[38:39], v130, 18
	v_cmp_gt_i32_e64 s[40:41], v130, 19
	v_cndmask_b32_e64 v88, v88, v131, s[34:35]
	v_cndmask_b32_e64 v89, v89, v131, s[36:37]
	v_cndmask_b32_e64 v90, v90, v131, s[38:39]
	v_cndmask_b32_e64 v91, v91, v131, s[40:41]
	v_cmp_gt_i32_e64 s[34:35], v130, 24
	v_cmp_gt_i32_e64 s[36:37], v130, 25
	v_cmp_gt_i32_e64 s[38:39], v130, 26
	v_cmp_gt_i32_e64 s[40:41], v130, 27
	v_cndmask_b32_e64 v92, v92, v131, s[34:35]
	v_cndmask_b32_e64 v93, v93, v131, s[36:37]
	v_cndmask_b32_e64 v94, v94, v131, s[38:39]
	v_cndmask_b32_e64 v95, v95, v131, s[40:41]
	v_max3_f32 v243, v243, v80, v81
	v_max3_f32 v243, v243, v82, v83
	v_max3_f32 v243, v243, v84, v85
	v_max3_f32 v243, v243, v86, v87
	v_max3_f32 v243, v243, v88, v89
	v_max3_f32 v243, v243, v90, v91
	v_max3_f32 v243, v243, v92, v93
	v_max3_f32 v243, v243, v94, v95
	s_branch .Ldil_p0L0_kdone0
.Ldil_p0L0_kskip0:
	s_max_u32 s99, s9, 0
	s_lshl_b32 s99, s99, 5
	s_addk_i32 s99, 0xff80
	v_add_u32_e32 v250, s99, v253
	v_lshl_add_u32 v250, v250, 10, v133
	global_load_dwordx4 v[0:3], v250, s[80:81]
	global_load_dwordx4 v[4:7], v250, s[82:83]
	global_load_dwordx4 v[8:11], v250, s[84:85]
	global_load_dwordx4 v[12:15], v250, s[86:87]
.Ldil_p0L0_kdone0:
	s_cmp_gt_u32 s9, 1
	s_cbranch_scc1 .Ldil_p0L0_kskip1
	s_waitcnt vmcnt(16)
	s_waitcnt lgkmcnt(0)
	ds_write_b128 v202, v[16:19]
	ds_write_b128 v202, v[20:23] offset:1152
	ds_write_b128 v202, v[24:27] offset:2304
	ds_write_b128 v202, v[28:31] offset:3456
	s_waitcnt lgkmcnt(0)
	s_max_u32 s99, s9, 1
	s_lshl_b32 s99, s99, 5
	s_addk_i32 s99, 0xff80
	v_add_u32_e32 v250, s99, v253
	v_lshl_add_u32 v250, v250, 10, v133
	global_load_dwordx4 v[16:19], v250, s[80:81]
	global_load_dwordx4 v[20:23], v250, s[82:83]
	global_load_dwordx4 v[24:27], v250, s[84:85]
	global_load_dwordx4 v[28:31], v250, s[86:87]
	ds_read_b128 v[152:155], v203
	ds_read_b128 v[156:159], v203 offset:32
	ds_read_b128 v[160:163], v203 offset:64
	ds_read_b128 v[164:167], v203 offset:96
	s_waitcnt lgkmcnt(0)
	v_mfma_f32_32x32x16_bf16 v[96:111], v[152:155], v[136:139], 0
	v_mfma_f32_32x32x16_bf16 v[96:111], v[156:159], v[140:143], v[96:111]
	v_mfma_f32_32x32x16_bf16 v[96:111], v[160:163], v[144:147], v[96:111]
	v_mfma_f32_32x32x16_bf16 v[96:111], v[164:167], v[148:151], v[96:111]
	s_nop 7
	s_nop 3
	v_max3_f32 v243, v243, v96, v97
	v_max3_f32 v243, v243, v98, v99
	v_max3_f32 v243, v243, v100, v101
	v_max3_f32 v243, v243, v102, v103
	v_max3_f32 v243, v243, v104, v105
	v_max3_f32 v243, v243, v106, v107
	v_max3_f32 v243, v243, v108, v109
	v_max3_f32 v243, v243, v110, v111
	s_branch .Ldil_p0L0_kdone1
.Ldil_p0L0_kskip1:
	s_max_u32 s99, s9, 1
	s_lshl_b32 s99, s99, 5
	s_addk_i32 s99, 0xff80
	v_add_u32_e32 v250, s99, v253
	v_lshl_add_u32 v250, v250, 10, v133
	global_load_dwordx4 v[16:19], v250, s[80:81]
	global_load_dwordx4 v[20:23], v250, s[82:83]
	global_load_dwordx4 v[24:27], v250, s[84:85]
	global_load_dwordx4 v[28:31], v250, s[86:87]
.Ldil_p0L0_kdone1:
	s_cmp_gt_u32 s9, 2
	s_cbranch_scc1 .Ldil_p0L0_kskip2
	s_waitcnt vmcnt(16)
	s_waitcnt lgkmcnt(0)
	ds_write_b128 v202, v[32:35]
	ds_write_b128 v202, v[36:39] offset:1152
	ds_write_b128 v202, v[40:43] offset:2304
	ds_write_b128 v202, v[44:47] offset:3456
	s_waitcnt lgkmcnt(0)
	s_max_u32 s99, s9, 2
	s_lshl_b32 s99, s99, 5
	s_addk_i32 s99, 0xff80
	v_add_u32_e32 v250, s99, v253
	v_lshl_add_u32 v250, v250, 10, v133
	global_load_dwordx4 v[32:35], v250, s[80:81]
	global_load_dwordx4 v[36:39], v250, s[82:83]
	global_load_dwordx4 v[40:43], v250, s[84:85]
	global_load_dwordx4 v[44:47], v250, s[86:87]
	ds_read_b128 v[152:155], v203
	ds_read_b128 v[156:159], v203 offset:32
	ds_read_b128 v[160:163], v203 offset:64
	ds_read_b128 v[164:167], v203 offset:96
	s_waitcnt lgkmcnt(0)
	v_mfma_f32_32x32x16_bf16 v[112:127], v[152:155], v[136:139], 0
	v_mfma_f32_32x32x16_bf16 v[112:127], v[156:159], v[140:143], v[112:127]
	v_mfma_f32_32x32x16_bf16 v[112:127], v[160:163], v[144:147], v[112:127]
	v_mfma_f32_32x32x16_bf16 v[112:127], v[164:167], v[148:151], v[112:127]
	s_nop 7
	s_nop 3
	v_max3_f32 v243, v243, v112, v113
	v_max3_f32 v243, v243, v114, v115
	v_max3_f32 v243, v243, v116, v117
	v_max3_f32 v243, v243, v118, v119
	v_max3_f32 v243, v243, v120, v121
	v_max3_f32 v243, v243, v122, v123
	v_max3_f32 v243, v243, v124, v125
	v_max3_f32 v243, v243, v126, v127
	s_branch .Ldil_p0L0_kdone2
.Ldil_p0L0_kskip2:
	s_max_u32 s99, s9, 2
	s_lshl_b32 s99, s99, 5
	s_addk_i32 s99, 0xff80
	v_add_u32_e32 v250, s99, v253
	v_lshl_add_u32 v250, v250, 10, v133
	global_load_dwordx4 v[32:35], v250, s[80:81]
	global_load_dwordx4 v[36:39], v250, s[82:83]
	global_load_dwordx4 v[40:43], v250, s[84:85]
	global_load_dwordx4 v[44:47], v250, s[86:87]
.Ldil_p0L0_kdone2:
	s_cmp_gt_u32 s9, 3
	s_cbranch_scc1 .Ldil_p0L0_kskip3
	s_waitcnt vmcnt(16)
	s_waitcnt lgkmcnt(0)
	ds_write_b128 v202, v[48:51]
	ds_write_b128 v202, v[52:55] offset:1152
	ds_write_b128 v202, v[56:59] offset:2304
	ds_write_b128 v202, v[60:63] offset:3456
	s_waitcnt lgkmcnt(0)
	s_max_u32 s99, s9, 3
	s_lshl_b32 s99, s99, 5
	s_addk_i32 s99, 0xff80
	v_add_u32_e32 v250, s99, v253
	v_lshl_add_u32 v250, v250, 10, v133
	global_load_dwordx4 v[48:51], v250, s[80:81]
	global_load_dwordx4 v[52:55], v250, s[82:83]
	global_load_dwordx4 v[56:59], v250, s[84:85]
	global_load_dwordx4 v[60:63], v250, s[86:87]
	ds_read_b128 v[152:155], v203
	ds_read_b128 v[156:159], v203 offset:32
	ds_read_b128 v[160:163], v203 offset:64
	ds_read_b128 v[164:167], v203 offset:96
	s_waitcnt lgkmcnt(0)
	v_mfma_f32_32x32x16_bf16 v[168:183], v[152:155], v[136:139], 0
	v_mfma_f32_32x32x16_bf16 v[168:183], v[156:159], v[140:143], v[168:183]
	v_mfma_f32_32x32x16_bf16 v[168:183], v[160:163], v[144:147], v[168:183]
	v_mfma_f32_32x32x16_bf16 v[168:183], v[164:167], v[148:151], v[168:183]
	s_nop 7
	s_nop 3
	v_max3_f32 v243, v243, v168, v169
	v_max3_f32 v243, v243, v170, v171
	v_max3_f32 v243, v243, v172, v173
	v_max3_f32 v243, v243, v174, v175
	v_max3_f32 v243, v243, v176, v177
	v_max3_f32 v243, v243, v178, v179
	v_max3_f32 v243, v243, v180, v181
	v_max3_f32 v243, v243, v182, v183
	s_branch .Ldil_p0L0_kdone3
.Ldil_p0L0_kskip3:
	s_max_u32 s99, s9, 3
	s_lshl_b32 s99, s99, 5
	s_addk_i32 s99, 0xff80
	v_add_u32_e32 v250, s99, v253
	v_lshl_add_u32 v250, v250, 10, v133
	global_load_dwordx4 v[48:51], v250, s[80:81]
	global_load_dwordx4 v[52:55], v250, s[82:83]
	global_load_dwordx4 v[56:59], v250, s[84:85]
	global_load_dwordx4 v[60:63], v250, s[86:87]
.Ldil_p0L0_kdone3:
	s_waitcnt vmcnt(16)
	s_waitcnt lgkmcnt(0)
	ds_write_b128 v202, v[64:67]
	ds_write_b128 v202, v[68:71] offset:1152
	ds_write_b128 v202, v[72:75] offset:2304
	ds_write_b128 v202, v[76:79] offset:3456
	s_waitcnt lgkmcnt(0)
	s_max_u32 s99, s9, 4
	s_lshl_b32 s99, s99, 5
	s_addk_i32 s99, 0xff80
	v_add_u32_e32 v250, s99, v253
	v_lshl_add_u32 v250, v250, 10, v133
	global_load_dwordx4 v[64:67], v250, s[80:81]
	global_load_dwordx4 v[68:71], v250, s[82:83]
	global_load_dwordx4 v[72:75], v250, s[84:85]
	global_load_dwordx4 v[76:79], v250, s[86:87]
	ds_read_b128 v[152:155], v203
	ds_read_b128 v[156:159], v203 offset:32
	ds_read_b128 v[160:163], v203 offset:64
	ds_read_b128 v[164:167], v203 offset:96
	s_waitcnt lgkmcnt(0)
	v_mfma_f32_32x32x16_bf16 v[184:199], v[152:155], v[136:139], 0
	v_mfma_f32_32x32x16_bf16 v[184:199], v[156:159], v[140:143], v[184:199]
	v_mfma_f32_32x32x16_bf16 v[184:199], v[160:163], v[144:147], v[184:199]
	v_mfma_f32_32x32x16_bf16 v[184:199], v[164:167], v[148:151], v[184:199]
	s_nop 7
	s_nop 3
	v_cmp_lt_i32_e64 s[34:35], v130, 0
	v_cmp_lt_i32_e64 s[36:37], v130, 1
	v_cmp_lt_i32_e64 s[38:39], v130, 2
	v_cmp_lt_i32_e64 s[40:41], v130, 3
	v_cndmask_b32_e64 v184, v184, v131, s[34:35]
	v_cndmask_b32_e64 v185, v185, v131, s[36:37]
	v_cndmask_b32_e64 v186, v186, v131, s[38:39]
	v_cndmask_b32_e64 v187, v187, v131, s[40:41]
	v_cmp_lt_i32_e64 s[34:35], v130, 8
	v_cmp_lt_i32_e64 s[36:37], v130, 9
	v_cmp_lt_i32_e64 s[38:39], v130, 10
	v_cmp_lt_i32_e64 s[40:41], v130, 11
	v_cndmask_b32_e64 v188, v188, v131, s[34:35]
	v_cndmask_b32_e64 v189, v189, v131, s[36:37]
	v_cndmask_b32_e64 v190, v190, v131, s[38:39]
	v_cndmask_b32_e64 v191, v191, v131, s[40:41]
	v_cmp_lt_i32_e64 s[34:35], v130, 16
	v_cmp_lt_i32_e64 s[36:37], v130, 17
	v_cmp_lt_i32_e64 s[38:39], v130, 18
	v_cmp_lt_i32_e64 s[40:41], v130, 19
	v_cndmask_b32_e64 v192, v192, v131, s[34:35]
	v_cndmask_b32_e64 v193, v193, v131, s[36:37]
	v_cndmask_b32_e64 v194, v194, v131, s[38:39]
	v_cndmask_b32_e64 v195, v195, v131, s[40:41]
	v_cmp_lt_i32_e64 s[34:35], v130, 24
	v_cmp_lt_i32_e64 s[36:37], v130, 25
	v_cmp_lt_i32_e64 s[38:39], v130, 26
	v_cmp_lt_i32_e64 s[40:41], v130, 27
	v_cndmask_b32_e64 v196, v196, v131, s[34:35]
	v_cndmask_b32_e64 v197, v197, v131, s[36:37]
	v_cndmask_b32_e64 v198, v198, v131, s[38:39]
	v_cndmask_b32_e64 v199, v199, v131, s[40:41]
	v_max3_f32 v243, v243, v184, v185
	v_max3_f32 v243, v243, v186, v187
	v_max3_f32 v243, v243, v188, v189
	v_max3_f32 v243, v243, v190, v191
	v_max3_f32 v243, v243, v192, v193
	v_max3_f32 v243, v243, v194, v195
	v_max3_f32 v243, v243, v196, v197
	v_max3_f32 v243, v243, v198, v199
	v_mov_b32_e32 v249, v243
	s_nop 1
	v_permlane32_swap_b32_e32 v243, v249
	s_waitcnt vmcnt(20)
	v_max3_f32 v246, v244, v243, v249
	v_sub_f32_e32 v247, v244, v246
	v_exp_f32_e32 v247, v247
	v_mov_b32_e32 v248, 0
	s_cmp_gt_u32 s9, 0
	s_cbranch_scc1 .Ldil_p0L0_eskip0
	v_sub_f32_e32 v80, v80, v246
	v_sub_f32_e32 v81, v81, v246
	v_exp_f32_e32 v80, v80
	v_sub_f32_e32 v82, v82, v246
	v_exp_f32_e32 v81, v81
	v_add_f32_e32 v248, v248, v80
	v_sub_f32_e32 v83, v83, v246
	v_exp_f32_e32 v82, v82
	v_add_f32_e32 v248, v248, v81
	v_sub_f32_e32 v84, v84, v246
	v_exp_f32_e32 v83, v83
	v_add_f32_e32 v248, v248, v82
	v_sub_f32_e32 v85, v85, v246
	v_exp_f32_e32 v84, v84
	v_add_f32_e32 v248, v248, v83
	v_sub_f32_e32 v86, v86, v246
	v_exp_f32_e32 v85, v85
	v_add_f32_e32 v248, v248, v84
	v_sub_f32_e32 v87, v87, v246
	v_exp_f32_e32 v86, v86
	v_add_f32_e32 v248, v248, v85
	v_sub_f32_e32 v88, v88, v246
	v_exp_f32_e32 v87, v87
	v_add_f32_e32 v248, v248, v86
	v_sub_f32_e32 v89, v89, v246
	v_exp_f32_e32 v88, v88
	v_add_f32_e32 v248, v248, v87
	v_sub_f32_e32 v90, v90, v246
	v_exp_f32_e32 v89, v89
	v_add_f32_e32 v248, v248, v88
	v_sub_f32_e32 v91, v91, v246
	v_exp_f32_e32 v90, v90
	v_add_f32_e32 v248, v248, v89
	v_sub_f32_e32 v92, v92, v246
	v_exp_f32_e32 v91, v91
	v_add_f32_e32 v248, v248, v90
	v_sub_f32_e32 v93, v93, v246
	v_exp_f32_e32 v92, v92
	v_add_f32_e32 v248, v248, v91
	v_sub_f32_e32 v94, v94, v246
	v_exp_f32_e32 v93, v93
	v_add_f32_e32 v248, v248, v92
	v_sub_f32_e32 v95, v95, v246
	v_exp_f32_e32 v94, v94
	v_add_f32_e32 v248, v248, v93
	v_exp_f32_e32 v95, v95
	v_add_f32_e32 v248, v248, v94
	s_nop 0
	v_add_f32_e32 v248, v248, v95

.Ldil_p0L0_eskip3:
	v_sub_f32_e32 v184, v184, v246
	v_sub_f32_e32 v185, v185, v246
	v_exp_f32_e32 v184, v184
	v_sub_f32_e32 v186, v186, v246
	v_exp_f32_e32 v185, v185
	v_add_f32_e32 v248, v248, v184
	v_sub_f32_e32 v187, v187, v246
	v_exp_f32_e32 v186, v186
	v_add_f32_e32 v248, v248, v185
	v_sub_f32_e32 v188, v188, v246
	v_exp_f32_e32 v187, v187
	v_add_f32_e32 v248, v248, v186
	v_sub_f32_e32 v189, v189, v246
	v_exp_f32_e32 v188, v188
	v_add_f32_e32 v248, v248, v187
	v_sub_f32_e32 v190, v190, v246
	v_exp_f32_e32 v189, v189
	v_add_f32_e32 v248, v248, v188
	v_sub_f32_e32 v191, v191, v246
	v_exp_f32_e32 v190, v190
	v_add_f32_e32 v248, v248, v189
	v_sub_f32_e32 v192, v192, v246
	v_exp_f32_e32 v191, v191
	v_add_f32_e32 v248, v248, v190
	v_sub_f32_e32 v193, v193, v246
	v_exp_f32_e32 v192, v192
	v_add_f32_e32 v248, v248, v191
	v_sub_f32_e32 v194, v194, v246
	v_exp_f32_e32 v193, v193
	v_add_f32_e32 v248, v248, v192
	v_sub_f32_e32 v195, v195, v246
	v_exp_f32_e32 v194, v194
	v_add_f32_e32 v248, v248, v193
	v_sub_f32_e32 v196, v196, v246
	v_exp_f32_e32 v195, v195
	v_add_f32_e32 v248, v248, v194
	v_sub_f32_e32 v197, v197, v246
	v_exp_f32_e32 v196, v196
	v_add_f32_e32 v248, v248, v195
	v_sub_f32_e32 v198, v198, v246
	v_exp_f32_e32 v197, v197
	v_add_f32_e32 v248, v248, v196
	v_sub_f32_e32 v199, v199, v246
	v_exp_f32_e32 v198, v198
	v_add_f32_e32 v248, v248, v197
	v_exp_f32_e32 v199, v199
	v_add_f32_e32 v248, v248, v198
	s_nop 0
	v_add_f32_e32 v248, v248, v199
	v_mov_b32_e32 v249, v248
	s_nop 1
	v_permlane32_swap_b32_e32 v248, v249
	s_nop 1
	v_add_f32_e32 v248, v248, v249
	v_fmac_f32_e32 v248, v245, v247
	v_add_u32_e32 v251, 2304, v201
	s_cmp_gt_u32 s9, 0
	s_cbranch_scc1 .Ldil_p0L0_pskip0
	s_waitcnt vmcnt(16)
	ds_write_b16 v200, v0
	ds_write_b16_d16_hi v200, v0 offset:72
	ds_write_b16 v200, v1 offset:144
	ds_write_b16_d16_hi v200, v1 offset:216
	ds_write_b16 v200, v2 offset:288
	ds_write_b16_d16_hi v200, v2 offset:360
	ds_write_b16 v200, v3 offset:432
	ds_write_b16_d16_hi v200, v3 offset:504
	ds_write_b16 v200, v4 offset:16
	ds_write_b16_d16_hi v200, v4 offset:88
	ds_write_b16 v200, v5 offset:160
	ds_write_b16_d16_hi v200, v5 offset:232
	ds_write_b16 v200, v6 offset:304
	ds_write_b16_d16_hi v200, v6 offset:376
	ds_write_b16 v200, v7 offset:448
	ds_write_b16_d16_hi v200, v7 offset:520
	ds_write_b16 v200, v8 offset:32
	ds_write_b16_d16_hi v200, v8 offset:104
	ds_write_b16 v200, v9 offset:176
	ds_write_b16_d16_hi v200, v9 offset:248
	ds_write_b16 v200, v10 offset:320
	ds_write_b16_d16_hi v200, v10 offset:392
	ds_write_b16 v200, v11 offset:464
	ds_write_b16_d16_hi v200, v11 offset:536
	ds_write_b16 v200, v12 offset:48
	ds_write_b16_d16_hi v200, v12 offset:120
	ds_write_b16 v200, v13 offset:192
	ds_write_b16_d16_hi v200, v13 offset:264
	ds_write_b16 v200, v14 offset:336
	ds_write_b16_d16_hi v200, v14 offset:408
	ds_write_b16 v200, v15 offset:480
	ds_write_b16_d16_hi v200, v15 offset:552
	v_cvt_pk_bf16_f32 v136, v80, v81
	v_cvt_pk_bf16_f32 v137, v82, v83
	v_cvt_pk_bf16_f32 v138, v84, v85
	v_cvt_pk_bf16_f32 v139, v86, v87
	v_cvt_pk_bf16_f32 v140, v88, v89
	v_cvt_pk_bf16_f32 v141, v90, v91
	v_cvt_pk_bf16_f32 v142, v92, v93
	v_cvt_pk_bf16_f32 v143, v94, v95
	s_waitcnt lgkmcnt(0)
	ds_read2_b64 v[152:155], v201 offset0:0 offset1:2
	ds_read2_b64 v[156:159], v251 offset0:0 offset1:2
	ds_read2_b64 v[160:163], v201 offset0:4 offset1:6
	ds_read2_b64 v[164:167], v251 offset0:4 offset1:6
	s_waitcnt lgkmcnt(0)
	v_mfma_f32_32x32x16_bf16 v[208:223], v[152:155], v[136:139], v[208:223]
	v_mfma_f32_32x32x16_bf16 v[224:239], v[156:159], v[136:139], v[224:239]
	v_mfma_f32_32x32x16_bf16 v[208:223], v[160:163], v[140:143], v[208:223]
	v_mfma_f32_32x32x16_bf16 v[224:239], v[164:167], v[140:143], v[224:239]
.Ldil_p0L0_pskip0:
	s_cmp_gt_u32 s9, 1
	s_cbranch_scc1 .Ldil_p0L0_pskip1
	s_waitcnt vmcnt(12)
	ds_write_b16 v200, v16
	ds_write_b16_d16_hi v200, v16 offset:72
	ds_write_b16 v200, v17 offset:144
	ds_write_b16_d16_hi v200, v17 offset:216
	ds_write_b16 v200, v18 offset:288
	ds_write_b16_d16_hi v200, v18 offset:360
	ds_write_b16 v200, v19 offset:432
	ds_write_b16_d16_hi v200, v19 offset:504
	ds_write_b16 v200, v20 offset:16
	ds_write_b16_d16_hi v200, v20 offset:88
	ds_write_b16 v200, v21 offset:160
	ds_write_b16_d16_hi v200, v21 offset:232
	ds_write_b16 v200, v22 offset:304
	ds_write_b16_d16_hi v200, v22 offset:376
	ds_write_b16 v200, v23 offset:448
	ds_write_b16_d16_hi v200, v23 offset:520
	ds_write_b16 v200, v24 offset:32
	ds_write_b16_d16_hi v200, v24 offset:104
	ds_write_b16 v200, v25 offset:176
	ds_write_b16_d16_hi v200, v25 offset:248
	ds_write_b16 v200, v26 offset:320
	ds_write_b16_d16_hi v200, v26 offset:392
	ds_write_b16 v200, v27 offset:464
	ds_write_b16_d16_hi v200, v27 offset:536
	ds_write_b16 v200, v28 offset:48
	ds_write_b16_d16_hi v200, v28 offset:120
	ds_write_b16 v200, v29 offset:192
	ds_write_b16_d16_hi v200, v29 offset:264
	ds_write_b16 v200, v30 offset:336
	ds_write_b16_d16_hi v200, v30 offset:408
	ds_write_b16 v200, v31 offset:480
	ds_write_b16_d16_hi v200, v31 offset:552
	v_cvt_pk_bf16_f32 v136, v96, v97
	v_cvt_pk_bf16_f32 v137, v98, v99
	v_cvt_pk_bf16_f32 v138, v100, v101
	v_cvt_pk_bf16_f32 v139, v102, v103
	v_cvt_pk_bf16_f32 v140, v104, v105
	v_cvt_pk_bf16_f32 v141, v106, v107
	v_cvt_pk_bf16_f32 v142, v108, v109
	v_cvt_pk_bf16_f32 v143, v110, v111
	s_waitcnt lgkmcnt(0)
	ds_read2_b64 v[152:155], v201 offset0:0 offset1:2
	ds_read2_b64 v[156:159], v251 offset0:0 offset1:2
	ds_read2_b64 v[160:163], v201 offset0:4 offset1:6
	ds_read2_b64 v[164:167], v251 offset0:4 offset1:6
	s_waitcnt lgkmcnt(0)
	v_mfma_f32_32x32x16_bf16 v[208:223], v[152:155], v[136:139], v[208:223]
	v_mfma_f32_32x32x16_bf16 v[224:239], v[156:159], v[136:139], v[224:239]
	v_mfma_f32_32x32x16_bf16 v[208:223], v[160:163], v[140:143], v[208:223]
	v_mfma_f32_32x32x16_bf16 v[224:239], v[164:167], v[140:143], v[224:239]
.Ldil_p0L0_pskip1:
	s_cmp_gt_u32 s9, 2
	s_cbranch_scc1 .Ldil_p0L0_pskip2
	s_waitcnt vmcnt(8)
	ds_write_b16 v200, v32
	ds_write_b16_d16_hi v200, v32 offset:72
	ds_write_b16 v200, v33 offset:144
	ds_write_b16_d16_hi v200, v33 offset:216
	ds_write_b16 v200, v34 offset:288
	ds_write_b16_d16_hi v200, v34 offset:360
	ds_write_b16 v200, v35 offset:432
	ds_write_b16_d16_hi v200, v35 offset:504
	ds_write_b16 v200, v36 offset:16
	ds_write_b16_d16_hi v200, v36 offset:88
	ds_write_b16 v200, v37 offset:160
	ds_write_b16_d16_hi v200, v37 offset:232
	ds_write_b16 v200, v38 offset:304
	ds_write_b16_d16_hi v200, v38 offset:376
	ds_write_b16 v200, v39 offset:448
	ds_write_b16_d16_hi v200, v39 offset:520
	ds_write_b16 v200, v40 offset:32
	ds_write_b16_d16_hi v200, v40 offset:104
	ds_write_b16 v200, v41 offset:176
	ds_write_b16_d16_hi v200, v41 offset:248
	ds_write_b16 v200, v42 offset:320
	ds_write_b16_d16_hi v200, v42 offset:392
	ds_write_b16 v200, v43 offset:464
	ds_write_b16_d16_hi v200, v43 offset:536
	ds_write_b16 v200, v44 offset:48
	ds_write_b16_d16_hi v200, v44 offset:120
	ds_write_b16 v200, v45 offset:192
	ds_write_b16_d16_hi v200, v45 offset:264
	ds_write_b16 v200, v46 offset:336
	ds_write_b16_d16_hi v200, v46 offset:408
	ds_write_b16 v200, v47 offset:480
	ds_write_b16_d16_hi v200, v47 offset:552
	v_cvt_pk_bf16_f32 v136, v112, v113
	v_cvt_pk_bf16_f32 v137, v114, v115
	v_cvt_pk_bf16_f32 v138, v116, v117
	v_cvt_pk_bf16_f32 v139, v118, v119
	v_cvt_pk_bf16_f32 v140, v120, v121
	v_cvt_pk_bf16_f32 v141, v122, v123
	v_cvt_pk_bf16_f32 v142, v124, v125
	v_cvt_pk_bf16_f32 v143, v126, v127
	s_waitcnt lgkmcnt(0)
	ds_read2_b64 v[152:155], v201 offset0:0 offset1:2
	ds_read2_b64 v[156:159], v251 offset0:0 offset1:2
	ds_read2_b64 v[160:163], v201 offset0:4 offset1:6
	ds_read2_b64 v[164:167], v251 offset0:4 offset1:6
	s_waitcnt lgkmcnt(0)
	v_mfma_f32_32x32x16_bf16 v[208:223], v[152:155], v[136:139], v[208:223]
	v_mfma_f32_32x32x16_bf16 v[224:239], v[156:159], v[136:139], v[224:239]
	v_mfma_f32_32x32x16_bf16 v[208:223], v[160:163], v[140:143], v[208:223]
	v_mfma_f32_32x32x16_bf16 v[224:239], v[164:167], v[140:143], v[224:239]
.Ldil_p0L0_pskip2:
	s_cmp_gt_u32 s9, 3
	s_cbranch_scc1 .Ldil_p0L0_pskip3
	s_waitcnt vmcnt(4)
	ds_write_b16 v200, v48
	ds_write_b16_d16_hi v200, v48 offset:72
	ds_write_b16 v200, v49 offset:144
	ds_write_b16_d16_hi v200, v49 offset:216
	ds_write_b16 v200, v50 offset:288
	ds_write_b16_d16_hi v200, v50 offset:360
	ds_write_b16 v200, v51 offset:432
	ds_write_b16_d16_hi v200, v51 offset:504
	ds_write_b16 v200, v52 offset:16
	ds_write_b16_d16_hi v200, v52 offset:88
	ds_write_b16 v200, v53 offset:160
	ds_write_b16_d16_hi v200, v53 offset:232
	ds_write_b16 v200, v54 offset:304
	ds_write_b16_d16_hi v200, v54 offset:376
	ds_write_b16 v200, v55 offset:448
	ds_write_b16_d16_hi v200, v55 offset:520
	ds_write_b16 v200, v56 offset:32
	ds_write_b16_d16_hi v200, v56 offset:104
	ds_write_b16 v200, v57 offset:176
	ds_write_b16_d16_hi v200, v57 offset:248
	ds_write_b16 v200, v58 offset:320
	ds_write_b16_d16_hi v200, v58 offset:392
	ds_write_b16 v200, v59 offset:464
	ds_write_b16_d16_hi v200, v59 offset:536
	ds_write_b16 v200, v60 offset:48
	ds_write_b16_d16_hi v200, v60 offset:120
	ds_write_b16 v200, v61 offset:192
	ds_write_b16_d16_hi v200, v61 offset:264
	ds_write_b16 v200, v62 offset:336
	ds_write_b16_d16_hi v200, v62 offset:408
	ds_write_b16 v200, v63 offset:480
	ds_write_b16_d16_hi v200, v63 offset:552
	v_cvt_pk_bf16_f32 v136, v168, v169
	v_cvt_pk_bf16_f32 v137, v170, v171
	v_cvt_pk_bf16_f32 v138, v172, v173
	v_cvt_pk_bf16_f32 v139, v174, v175
	v_cvt_pk_bf16_f32 v140, v176, v177
	v_cvt_pk_bf16_f32 v141, v178, v179
	v_cvt_pk_bf16_f32 v142, v180, v181
	v_cvt_pk_bf16_f32 v143, v182, v183
	s_waitcnt lgkmcnt(0)
	ds_read2_b64 v[152:155], v201 offset0:0 offset1:2
	ds_read2_b64 v[156:159], v251 offset0:0 offset1:2
	ds_read2_b64 v[160:163], v201 offset0:4 offset1:6
	ds_read2_b64 v[164:167], v251 offset0:4 offset1:6
	s_waitcnt lgkmcnt(0)
	v_mfma_f32_32x32x16_bf16 v[208:223], v[152:155], v[136:139], v[208:223]
	v_mfma_f32_32x32x16_bf16 v[224:239], v[156:159], v[136:139], v[224:239]
	v_mfma_f32_32x32x16_bf16 v[208:223], v[160:163], v[140:143], v[208:223]
	v_mfma_f32_32x32x16_bf16 v[224:239], v[164:167], v[140:143], v[224:239]
.Ldil_p0L0_pskip3:
	s_waitcnt vmcnt(0)
	ds_write_b16 v200, v64
	ds_write_b16_d16_hi v200, v64 offset:72
	ds_write_b16 v200, v65 offset:144
	ds_write_b16_d16_hi v200, v65 offset:216
	ds_write_b16 v200, v66 offset:288
	ds_write_b16_d16_hi v200, v66 offset:360
	ds_write_b16 v200, v67 offset:432
	ds_write_b16_d16_hi v200, v67 offset:504
	ds_write_b16 v200, v68 offset:16
	ds_write_b16_d16_hi v200, v68 offset:88
	ds_write_b16 v200, v69 offset:160
	ds_write_b16_d16_hi v200, v69 offset:232
	ds_write_b16 v200, v70 offset:304
	ds_write_b16_d16_hi v200, v70 offset:376
	ds_write_b16 v200, v71 offset:448
	ds_write_b16_d16_hi v200, v71 offset:520
	ds_write_b16 v200, v72 offset:32
	ds_write_b16_d16_hi v200, v72 offset:104
	ds_write_b16 v200, v73 offset:176
	ds_write_b16_d16_hi v200, v73 offset:248
	ds_write_b16 v200, v74 offset:320
	ds_write_b16_d16_hi v200, v74 offset:392
	ds_write_b16 v200, v75 offset:464
	ds_write_b16_d16_hi v200, v75 offset:536
	ds_write_b16 v200, v76 offset:48
	ds_write_b16_d16_hi v200, v76 offset:120
	ds_write_b16 v200, v77 offset:192
	ds_write_b16_d16_hi v200, v77 offset:264
	ds_write_b16 v200, v78 offset:336
	ds_write_b16_d16_hi v200, v78 offset:408
	ds_write_b16 v200, v79 offset:480
	ds_write_b16_d16_hi v200, v79 offset:552
	v_cvt_pk_bf16_f32 v136, v184, v185
	v_cvt_pk_bf16_f32 v137, v186, v187
	v_cvt_pk_bf16_f32 v138, v188, v189
	v_cvt_pk_bf16_f32 v139, v190, v191
	v_cvt_pk_bf16_f32 v140, v192, v193
	v_cvt_pk_bf16_f32 v141, v194, v195
	v_cvt_pk_bf16_f32 v142, v196, v197
	v_cvt_pk_bf16_f32 v143, v198, v199
	s_waitcnt lgkmcnt(0)
	ds_read2_b64 v[152:155], v201 offset0:0 offset1:2
	ds_read2_b64 v[156:159], v251 offset0:0 offset1:2
	ds_read2_b64 v[160:163], v201 offset0:4 offset1:6
	ds_read2_b64 v[164:167], v251 offset0:4 offset1:6
	s_waitcnt lgkmcnt(0)
	v_mfma_f32_32x32x16_bf16 v[208:223], v[152:155], v[136:139], v[208:223]
	v_mfma_f32_32x32x16_bf16 v[224:239], v[156:159], v[136:139], v[224:239]
	v_mfma_f32_32x32x16_bf16 v[208:223], v[160:163], v[140:143], v[208:223]
	v_mfma_f32_32x32x16_bf16 v[224:239], v[164:167], v[140:143], v[224:239]
	s_nop 7
	s_nop 3
	ds_write_b128 v205, v[208:211]
	ds_write_b128 v205, v[212:215] offset:32
	ds_write_b128 v205, v[216:219] offset:64
	ds_write_b128 v205, v[220:223] offset:96
	ds_write_b128 v205, v[224:227] offset:128
	ds_write_b128 v205, v[228:231] offset:160
	ds_write_b128 v205, v[232:235] offset:192
	ds_write_b128 v205, v[236:239] offset:224
	s_waitcnt lgkmcnt(0)
	ds_read_b128 v[208:211], v204
	ds_read_b128 v[212:215], v204 offset:1088
	ds_read_b128 v[216:219], v204 offset:2176
	ds_read_b128 v[220:223], v204 offset:3264
	ds_read_b128 v[224:227], v204 offset:4352
	ds_read_b128 v[228:231], v204 offset:5440
	ds_read_b128 v[232:235], v204 offset:6528
	ds_read_b128 v[236:239], v204 offset:7616
	s_waitcnt lgkmcnt(0)
	global_store_dwordx4 v241, v[208:211], s[56:57]
	v_add_u32_e32 v252, 0x2000, v241
	global_store_dwordx4 v252, v[212:215], s[56:57]
	v_add_u32_e32 v252, 0x4000, v241
	global_store_dwordx4 v252, v[216:219], s[56:57]
	v_add_u32_e32 v252, 0x6000, v241
	global_store_dwordx4 v252, v[220:223], s[56:57]
	v_add_u32_e32 v252, 0x8000, v241
	global_store_dwordx4 v252, v[224:227], s[56:57]
	v_add_u32_e32 v252, 0xa000, v241
	global_store_dwordx4 v252, v[228:231], s[56:57]
	v_add_u32_e32 v252, 0xc000, v241
	global_store_dwordx4 v252, v[232:235], s[56:57]
	v_add_u32_e32 v252, 0xe000, v241
	global_store_dwordx4 v252, v[236:239], s[56:57]
	s_mov_b64 exec, 0xffffffff
	global_store_dword v240, v246, s[58:59]
	global_store_dword v240, v248, s[60:61]
	s_mov_b64 exec, -1
	s_lshl_b32 s99, s33, 3
	s_add_i32 s98, s98, s99
	s_cmpk_lt_i32 s98, 0x2000
	s_cbranch_scc1 .Ldil_p0L0_loop
	s_waitcnt lgkmcnt(0)
	s_branch .LBB0_348

.LBB0_410:
	s_mov_b64 exec, -1
	s_load_dwordx2 s[100:101], s[0:1], 0xf0
	s_mov_b32 s98, s94
	v_and_b32_e32 v128, 31, v206
	v_bfe_u32 v249, v206, 5, 1
	v_lshlrev_b32_e32 v129, 4, v249
	v_lshlrev_b32_e32 v250, 2, v249
	v_sub_u32_e32 v130, v128, v250
	v_mov_b32_e32 v131, 0xf149f2ca
	v_and_b32_e32 v133, 7, v206
	v_lshlrev_b32_e32 v133, 4, v133
	v_and_b32_e32 v134, 15, v206
	v_lshlrev_b32_e32 v134, 4, v134
	v_lshrrev_b32_e32 v251, 6, v206
	v_lshlrev_b32_e32 v251, 14, v251
	v_and_b32_e32 v252, 7, v206
	v_mul_u32_u24_e32 v252, 0x240, v252
	v_bfe_u32 v200, v206, 3, 3
	v_lshl_add_u32 v200, v200, 1, v252
	v_add_u32_e32 v200, v200, v251
	v_mul_u32_u24_e32 v252, 72, v128
	v_lshl_add_u32 v201, v249, 3, v252
	v_add_u32_e32 v201, v201, v251
	v_bfe_u32 v252, v206, 3, 3
	v_mul_u32_u24_e32 v252, 144, v252
	v_add3_u32 v202, v252, v133, v251
	v_add_u32_e32 v202, 4608, v202
	v_mul_u32_u24_e32 v252, 144, v128
	v_add3_u32 v203, v252, v129, v251
	v_add_u32_e32 v203, 4608, v203
	v_bfe_u32 v252, v206, 4, 2
	v_mul_u32_u24_e32 v252, 272, v252
	v_add3_u32 v204, v252, v134, v251
	v_add_u32_e32 v204, 4608, v204
	v_mul_u32_u24_e32 v252, 272, v128
	v_add3_u32 v205, v252, v129, v251
	v_add_u32_e32 v205, 4608, v205
	s_waitcnt lgkmcnt(0)
.Ldil_p1L0_loop:
	s_and_b32 s4, s98, 31
	s_bfe_u32 s5, s98, 0x20005
	s_lshr_b32 s6, s98, 10
	s_and_b32 s7, s98, 0x380
	s_lshl_b32 s99, s6, 12
	s_add_u32 s8, s99, s5
	s_sub_u32 s9, 4, s4
	s_max_i32 s9, s9, 0
	s_lshl_b32 s4, s4, 5
	v_add_u32_e32 v135, s4, v128
	s_lshl_b32 s99, s8, 10
	s_add_u32 s99, s99, s7
	s_add_u32 s64, s99, 0x16000000
	s_add_u32 s64, s100, s64
	s_addc_u32 s65, s101, 0
	s_add_u32 s72, s64, 0x2000000
	s_addc_u32 s73, s65, 0
	s_add_u32 s52, s72, 0x2000000
	s_addc_u32 s53, s73, 0
	s_mov_b64 s[80:81], s[52:53]
	s_add_u32 s82, s80, 0x8000
	s_addc_u32 s83, s81, 0
	s_add_u32 s84, s82, 0x8000
	s_addc_u32 s85, s83, 0
	s_add_u32 s86, s84, 0x8000
	s_addc_u32 s87, s85, 0
	s_add_u32 s66, s64, 0x8000
	s_addc_u32 s67, s65, 0
	s_add_u32 s74, s72, 0x8000
	s_addc_u32 s75, s73, 0
	s_add_u32 s68, s66, 0x8000
	s_addc_u32 s69, s67, 0
	s_add_u32 s76, s74, 0x8000
	s_addc_u32 s77, s75, 0
	s_add_u32 s70, s68, 0x8000
	s_addc_u32 s71, s69, 0
	s_add_u32 s78, s76, 0x8000
	s_addc_u32 s79, s77, 0
	v_bfe_u32 v249, v206, 3, 3
	v_add_u32_e32 v249, s4, v249
	v_mov_b32_e32 v253, v249
	v_lshl_add_u32 v250, v249, 12, v133
	global_load_dwordx4 v[152:155], v250, s[64:65]
	global_load_dwordx4 v[156:159], v250, s[66:67]
	global_load_dwordx4 v[160:163], v250, s[68:69]
	global_load_dwordx4 v[164:167], v250, s[70:71]
	s_max_u32 s99, s9, 0
	s_lshl_b32 s99, s99, 5
	s_addk_i32 s99, 0xff80
	v_add_u32_e32 v250, s99, v249
	v_lshl_add_u32 v250, v250, 12, v133
	global_load_dwordx4 v[0:3], v250, s[72:73]
	global_load_dwordx4 v[4:7], v250, s[74:75]
	global_load_dwordx4 v[8:11], v250, s[76:77]
	global_load_dwordx4 v[12:15], v250, s[78:79]
	s_max_u32 s99, s9, 1
	s_lshl_b32 s99, s99, 5
	s_addk_i32 s99, 0xff80
	v_add_u32_e32 v250, s99, v249
	v_lshl_add_u32 v250, v250, 12, v133
	global_load_dwordx4 v[16:19], v250, s[72:73]
	global_load_dwordx4 v[20:23], v250, s[74:75]
	global_load_dwordx4 v[24:27], v250, s[76:77]
	global_load_dwordx4 v[28:31], v250, s[78:79]
	s_max_u32 s99, s9, 2
	s_lshl_b32 s99, s99, 5
	s_addk_i32 s99, 0xff80
	v_add_u32_e32 v250, s99, v249
	v_lshl_add_u32 v250, v250, 12, v133
	global_load_dwordx4 v[32:35], v250, s[72:73]
	global_load_dwordx4 v[36:39], v250, s[74:75]
	global_load_dwordx4 v[40:43], v250, s[76:77]
	global_load_dwordx4 v[44:47], v250, s[78:79]
	s_max_u32 s99, s9, 3
	s_lshl_b32 s99, s99, 5
	s_addk_i32 s99, 0xff80
	v_add_u32_e32 v250, s99, v249
	v_lshl_add_u32 v250, v250, 12, v133
	global_load_dwordx4 v[48:51], v250, s[72:73]
	global_load_dwordx4 v[52:55], v250, s[74:75]
	global_load_dwordx4 v[56:59], v250, s[76:77]
	global_load_dwordx4 v[60:63], v250, s[78:79]
	s_max_u32 s99, s9, 4
	s_lshl_b32 s99, s99, 5
	s_addk_i32 s99, 0xff80
	v_add_u32_e32 v250, s99, v249
	v_lshl_add_u32 v250, v250, 12, v133
	global_load_dwordx4 v[64:67], v250, s[72:73]
	global_load_dwordx4 v[68:71], v250, s[74:75]
	global_load_dwordx4 v[72:75], v250, s[76:77]
	global_load_dwordx4 v[76:79], v250, s[78:79]
	s_lshl_b32 s99, s8, 5
	s_lshr_b32 s58, s7, 5
	s_add_u32 s99, s99, s58
	s_add_u32 s99, s99, 0x400000
	s_add_u32 s58, s100, s99
	s_addc_u32 s59, s101, 0
	s_add_u32 s60, s58, 0x100000
	s_addc_u32 s61, s59, 0
	v_lshlrev_b32_e32 v240, 7, v135
	s_lshl_b32 s99, s8, 11
	s_lshl_b32 s56, s7, 1
	s_add_u32 s99, s99, s56
	s_add_u32 s99, s99, 0x8000000
	s_add_u32 s56, s100, s99
	s_addc_u32 s57, s101, 0
	v_bfe_u32 v251, v206, 4, 2
	v_add_u32_e32 v251, s4, v251
	v_lshl_add_u32 v241, v251, 13, v134
	global_load_dword v244, v240, s[58:59]
	global_load_dword v245, v240, s[60:61]
	global_load_dwordx4 v[208:211], v241, s[56:57]
	v_add_u32_e32 v252, 0x8000, v241
	global_load_dwordx4 v[212:215], v252, s[56:57]
	v_add_u32_e32 v252, 0x10000, v241
	global_load_dwordx4 v[216:219], v252, s[56:57]
	v_add_u32_e32 v252, 0x18000, v241
	global_load_dwordx4 v[220:223], v252, s[56:57]
	v_add_u32_e32 v252, 0x20000, v241
	global_load_dwordx4 v[224:227], v252, s[56:57]
	v_add_u32_e32 v252, 0x28000, v241
	global_load_dwordx4 v[228:231], v252, s[56:57]
	v_add_u32_e32 v252, 0x30000, v241
	global_load_dwordx4 v[232:235], v252, s[56:57]
	v_add_u32_e32 v252, 0x38000, v241
	global_load_dwordx4 v[236:239], v252, s[56:57]
	v_mov_b32_e32 v243, v131
	s_waitcnt vmcnt(30)
	ds_write_b128 v202, v[152:155]
	ds_write_b128 v202, v[156:159] offset:1152
	ds_write_b128 v202, v[160:163] offset:2304
	ds_write_b128 v202, v[164:167] offset:3456
	s_waitcnt lgkmcnt(0)
	ds_read_b128 v[136:139], v203
	ds_read_b128 v[140:143], v203 offset:32
	ds_read_b128 v[144:147], v203 offset:64
	ds_read_b128 v[148:151], v203 offset:96
	s_cmp_gt_u32 s9, 0
	s_cbranch_scc1 .Ldil_p1L0_kskip0
	s_waitcnt vmcnt(26)
	s_waitcnt lgkmcnt(0)
	ds_write_b128 v202, v[0:3]
	ds_write_b128 v202, v[4:7] offset:1152
	ds_write_b128 v202, v[8:11] offset:2304
	ds_write_b128 v202, v[12:15] offset:3456
	s_waitcnt lgkmcnt(0)
	s_max_u32 s99, s9, 0
	s_lshl_b32 s99, s99, 5
	s_addk_i32 s99, 0xff80
	v_add_u32_e32 v250, s99, v253
	v_lshl_add_u32 v250, v250, 12, v133
	global_load_dwordx4 v[0:3], v250, s[80:81]
	global_load_dwordx4 v[4:7], v250, s[82:83]
	global_load_dwordx4 v[8:11], v250, s[84:85]
	global_load_dwordx4 v[12:15], v250, s[86:87]
	ds_read_b128 v[152:155], v203
	ds_read_b128 v[156:159], v203 offset:32
	ds_read_b128 v[160:163], v203 offset:64
	ds_read_b128 v[164:167], v203 offset:96
	s_waitcnt lgkmcnt(0)
	v_mfma_f32_32x32x16_bf16 v[80:95], v[152:155], v[136:139], 0
	v_mfma_f32_32x32x16_bf16 v[80:95], v[156:159], v[140:143], v[80:95]
	v_mfma_f32_32x32x16_bf16 v[80:95], v[160:163], v[144:147], v[80:95]
	v_mfma_f32_32x32x16_bf16 v[80:95], v[164:167], v[148:151], v[80:95]
	s_nop 7
	s_nop 3
	v_cmp_gt_i32_e64 s[34:35], v130, 0
	v_cmp_gt_i32_e64 s[36:37], v130, 1
	v_cmp_gt_i32_e64 s[38:39], v130, 2
	v_cmp_gt_i32_e64 s[40:41], v130, 3
	v_cndmask_b32_e64 v80, v80, v131, s[34:35]
	v_cndmask_b32_e64 v81, v81, v131, s[36:37]
	v_cndmask_b32_e64 v82, v82, v131, s[38:39]
	v_cndmask_b32_e64 v83, v83, v131, s[40:41]
	v_cmp_gt_i32_e64 s[34:35], v130, 8
	v_cmp_gt_i32_e64 s[36:37], v130, 9
	v_cmp_gt_i32_e64 s[38:39], v130, 10
	v_cmp_gt_i32_e64 s[40:41], v130, 11
	v_cndmask_b32_e64 v84, v84, v131, s[34:35]
	v_cndmask_b32_e64 v85, v85, v131, s[36:37]
	v_cndmask_b32_e64 v86, v86, v131, s[38:39]
	v_cndmask_b32_e64 v87, v87, v131, s[40:41]
	v_cmp_gt_i32_e64 s[34:35], v130, 16
	v_cmp_gt_i32_e64 s[36:37], v130, 17
	v_cmp_gt_i32_e64 s[38:39], v130, 18
	v_cmp_gt_i32_e64 s[40:41], v130, 19
	v_cndmask_b32_e64 v88, v88, v131, s[34:35]
	v_cndmask_b32_e64 v89, v89, v131, s[36:37]
	v_cndmask_b32_e64 v90, v90, v131, s[38:39]
	v_cndmask_b32_e64 v91, v91, v131, s[40:41]
	v_cmp_gt_i32_e64 s[34:35], v130, 24
	v_cmp_gt_i32_e64 s[36:37], v130, 25
	v_cmp_gt_i32_e64 s[38:39], v130, 26
	v_cmp_gt_i32_e64 s[40:41], v130, 27
	v_cndmask_b32_e64 v92, v92, v131, s[34:35]
	v_cndmask_b32_e64 v93, v93, v131, s[36:37]
	v_cndmask_b32_e64 v94, v94, v131, s[38:39]
	v_cndmask_b32_e64 v95, v95, v131, s[40:41]
	v_max3_f32 v243, v243, v80, v81
	v_max3_f32 v243, v243, v82, v83
	v_max3_f32 v243, v243, v84, v85
	v_max3_f32 v243, v243, v86, v87
	v_max3_f32 v243, v243, v88, v89
	v_max3_f32 v243, v243, v90, v91
	v_max3_f32 v243, v243, v92, v93
	v_max3_f32 v243, v243, v94, v95
	s_branch .Ldil_p1L0_kdone0
.Ldil_p1L0_kskip0:
	s_max_u32 s99, s9, 0
	s_lshl_b32 s99, s99, 5
	s_addk_i32 s99, 0xff80
	v_add_u32_e32 v250, s99, v253
	v_lshl_add_u32 v250, v250, 12, v133
	global_load_dwordx4 v[0:3], v250, s[80:81]
	global_load_dwordx4 v[4:7], v250, s[82:83]
	global_load_dwordx4 v[8:11], v250, s[84:85]
	global_load_dwordx4 v[12:15], v250, s[86:87]
.Ldil_p1L0_kdone0:
	s_cmp_gt_u32 s9, 1
	s_cbranch_scc1 .Ldil_p1L0_kskip1
	s_waitcnt vmcnt(26)
	s_waitcnt lgkmcnt(0)
	ds_write_b128 v202, v[16:19]
	ds_write_b128 v202, v[20:23] offset:1152
	ds_write_b128 v202, v[24:27] offset:2304
	ds_write_b128 v202, v[28:31] offset:3456
	s_waitcnt lgkmcnt(0)
	s_max_u32 s99, s9, 1
	s_lshl_b32 s99, s99, 5
	s_addk_i32 s99, 0xff80
	v_add_u32_e32 v250, s99, v253
	v_lshl_add_u32 v250, v250, 12, v133
	global_load_dwordx4 v[16:19], v250, s[80:81]
	global_load_dwordx4 v[20:23], v250, s[82:83]
	global_load_dwordx4 v[24:27], v250, s[84:85]
	global_load_dwordx4 v[28:31], v250, s[86:87]
	ds_read_b128 v[152:155], v203
	ds_read_b128 v[156:159], v203 offset:32
	ds_read_b128 v[160:163], v203 offset:64
	ds_read_b128 v[164:167], v203 offset:96
	s_waitcnt lgkmcnt(0)
	v_mfma_f32_32x32x16_bf16 v[96:111], v[152:155], v[136:139], 0
	v_mfma_f32_32x32x16_bf16 v[96:111], v[156:159], v[140:143], v[96:111]
	v_mfma_f32_32x32x16_bf16 v[96:111], v[160:163], v[144:147], v[96:111]
	v_mfma_f32_32x32x16_bf16 v[96:111], v[164:167], v[148:151], v[96:111]
	s_nop 7
	s_nop 3
	v_max3_f32 v243, v243, v96, v97
	v_max3_f32 v243, v243, v98, v99
	v_max3_f32 v243, v243, v100, v101
	v_max3_f32 v243, v243, v102, v103
	v_max3_f32 v243, v243, v104, v105
	v_max3_f32 v243, v243, v106, v107
	v_max3_f32 v243, v243, v108, v109
	v_max3_f32 v243, v243, v110, v111
	s_branch .Ldil_p1L0_kdone1
.Ldil_p1L0_kskip1:
	s_max_u32 s99, s9, 1
	s_lshl_b32 s99, s99, 5
	s_addk_i32 s99, 0xff80
	v_add_u32_e32 v250, s99, v253
	v_lshl_add_u32 v250, v250, 12, v133
	global_load_dwordx4 v[16:19], v250, s[80:81]
	global_load_dwordx4 v[20:23], v250, s[82:83]
	global_load_dwordx4 v[24:27], v250, s[84:85]
	global_load_dwordx4 v[28:31], v250, s[86:87]
.Ldil_p1L0_kdone1:
	s_cmp_gt_u32 s9, 2
	s_cbranch_scc1 .Ldil_p1L0_kskip2
	s_waitcnt vmcnt(26)
	s_waitcnt lgkmcnt(0)
	ds_write_b128 v202, v[32:35]
	ds_write_b128 v202, v[36:39] offset:1152
	ds_write_b128 v202, v[40:43] offset:2304
	ds_write_b128 v202, v[44:47] offset:3456
	s_waitcnt lgkmcnt(0)
	s_max_u32 s99, s9, 2
	s_lshl_b32 s99, s99, 5
	s_addk_i32 s99, 0xff80
	v_add_u32_e32 v250, s99, v253
	v_lshl_add_u32 v250, v250, 12, v133
	global_load_dwordx4 v[32:35], v250, s[80:81]
	global_load_dwordx4 v[36:39], v250, s[82:83]
	global_load_dwordx4 v[40:43], v250, s[84:85]
	global_load_dwordx4 v[44:47], v250, s[86:87]
	ds_read_b128 v[152:155], v203
	ds_read_b128 v[156:159], v203 offset:32
	ds_read_b128 v[160:163], v203 offset:64
	ds_read_b128 v[164:167], v203 offset:96
	s_waitcnt lgkmcnt(0)
	v_mfma_f32_32x32x16_bf16 v[112:127], v[152:155], v[136:139], 0
	v_mfma_f32_32x32x16_bf16 v[112:127], v[156:159], v[140:143], v[112:127]
	v_mfma_f32_32x32x16_bf16 v[112:127], v[160:163], v[144:147], v[112:127]
	v_mfma_f32_32x32x16_bf16 v[112:127], v[164:167], v[148:151], v[112:127]
	s_nop 7
	s_nop 3
	v_max3_f32 v243, v243, v112, v113
	v_max3_f32 v243, v243, v114, v115
	v_max3_f32 v243, v243, v116, v117
	v_max3_f32 v243, v243, v118, v119
	v_max3_f32 v243, v243, v120, v121
	v_max3_f32 v243, v243, v122, v123
	v_max3_f32 v243, v243, v124, v125
	v_max3_f32 v243, v243, v126, v127
	s_branch .Ldil_p1L0_kdone2
.Ldil_p1L0_kskip2:
	s_max_u32 s99, s9, 2
	s_lshl_b32 s99, s99, 5
	s_addk_i32 s99, 0xff80
	v_add_u32_e32 v250, s99, v253
	v_lshl_add_u32 v250, v250, 12, v133
	global_load_dwordx4 v[32:35], v250, s[80:81]
	global_load_dwordx4 v[36:39], v250, s[82:83]
	global_load_dwordx4 v[40:43], v250, s[84:85]
	global_load_dwordx4 v[44:47], v250, s[86:87]
.Ldil_p1L0_kdone2:
	s_cmp_gt_u32 s9, 3
	s_cbranch_scc1 .Ldil_p1L0_kskip3
	s_waitcnt vmcnt(26)
	s_waitcnt lgkmcnt(0)
	ds_write_b128 v202, v[48:51]
	ds_write_b128 v202, v[52:55] offset:1152
	ds_write_b128 v202, v[56:59] offset:2304
	ds_write_b128 v202, v[60:63] offset:3456
	s_waitcnt lgkmcnt(0)
	s_max_u32 s99, s9, 3
	s_lshl_b32 s99, s99, 5
	s_addk_i32 s99, 0xff80
	v_add_u32_e32 v250, s99, v253
	v_lshl_add_u32 v250, v250, 12, v133
	global_load_dwordx4 v[48:51], v250, s[80:81]
	global_load_dwordx4 v[52:55], v250, s[82:83]
	global_load_dwordx4 v[56:59], v250, s[84:85]
	global_load_dwordx4 v[60:63], v250, s[86:87]
	ds_read_b128 v[152:155], v203
	ds_read_b128 v[156:159], v203 offset:32
	ds_read_b128 v[160:163], v203 offset:64
	ds_read_b128 v[164:167], v203 offset:96
	s_waitcnt lgkmcnt(0)
	v_mfma_f32_32x32x16_bf16 v[168:183], v[152:155], v[136:139], 0
	v_mfma_f32_32x32x16_bf16 v[168:183], v[156:159], v[140:143], v[168:183]
	v_mfma_f32_32x32x16_bf16 v[168:183], v[160:163], v[144:147], v[168:183]
	v_mfma_f32_32x32x16_bf16 v[168:183], v[164:167], v[148:151], v[168:183]
	s_nop 7
	s_nop 3
	v_max3_f32 v243, v243, v168, v169
	v_max3_f32 v243, v243, v170, v171
	v_max3_f32 v243, v243, v172, v173
	v_max3_f32 v243, v243, v174, v175
	v_max3_f32 v243, v243, v176, v177
	v_max3_f32 v243, v243, v178, v179
	v_max3_f32 v243, v243, v180, v181
	v_max3_f32 v243, v243, v182, v183
	s_branch .Ldil_p1L0_kdone3
.Ldil_p1L0_kskip3:
	s_max_u32 s99, s9, 3
	s_lshl_b32 s99, s99, 5
	s_addk_i32 s99, 0xff80
	v_add_u32_e32 v250, s99, v253
	v_lshl_add_u32 v250, v250, 12, v133
	global_load_dwordx4 v[48:51], v250, s[80:81]
	global_load_dwordx4 v[52:55], v250, s[82:83]
	global_load_dwordx4 v[56:59], v250, s[84:85]
	global_load_dwordx4 v[60:63], v250, s[86:87]
.Ldil_p1L0_kdone3:
	s_waitcnt vmcnt(26)
	s_waitcnt lgkmcnt(0)
	ds_write_b128 v202, v[64:67]
	ds_write_b128 v202, v[68:71] offset:1152
	ds_write_b128 v202, v[72:75] offset:2304
	ds_write_b128 v202, v[76:79] offset:3456
	s_waitcnt lgkmcnt(0)
	s_max_u32 s99, s9, 4
	s_lshl_b32 s99, s99, 5
	s_addk_i32 s99, 0xff80
	v_add_u32_e32 v250, s99, v253
	v_lshl_add_u32 v250, v250, 12, v133
	global_load_dwordx4 v[64:67], v250, s[80:81]
	global_load_dwordx4 v[68:71], v250, s[82:83]
	global_load_dwordx4 v[72:75], v250, s[84:85]
	global_load_dwordx4 v[76:79], v250, s[86:87]
	ds_read_b128 v[152:155], v203
	ds_read_b128 v[156:159], v203 offset:32
	ds_read_b128 v[160:163], v203 offset:64
	ds_read_b128 v[164:167], v203 offset:96
	s_waitcnt lgkmcnt(0)
	v_mfma_f32_32x32x16_bf16 v[184:199], v[152:155], v[136:139], 0
	v_mfma_f32_32x32x16_bf16 v[184:199], v[156:159], v[140:143], v[184:199]
	v_mfma_f32_32x32x16_bf16 v[184:199], v[160:163], v[144:147], v[184:199]
	v_mfma_f32_32x32x16_bf16 v[184:199], v[164:167], v[148:151], v[184:199]
	s_nop 7
	s_nop 3
	v_cmp_lt_i32_e64 s[34:35], v130, 0
	v_cmp_lt_i32_e64 s[36:37], v130, 1
	v_cmp_lt_i32_e64 s[38:39], v130, 2
	v_cmp_lt_i32_e64 s[40:41], v130, 3
	v_cndmask_b32_e64 v184, v184, v131, s[34:35]
	v_cndmask_b32_e64 v185, v185, v131, s[36:37]
	v_cndmask_b32_e64 v186, v186, v131, s[38:39]
	v_cndmask_b32_e64 v187, v187, v131, s[40:41]
	v_cmp_lt_i32_e64 s[34:35], v130, 8
	v_cmp_lt_i32_e64 s[36:37], v130, 9
	v_cmp_lt_i32_e64 s[38:39], v130, 10
	v_cmp_lt_i32_e64 s[40:41], v130, 11
	v_cndmask_b32_e64 v188, v188, v131, s[34:35]
	v_cndmask_b32_e64 v189, v189, v131, s[36:37]
	v_cndmask_b32_e64 v190, v190, v131, s[38:39]
	v_cndmask_b32_e64 v191, v191, v131, s[40:41]
	v_cmp_lt_i32_e64 s[34:35], v130, 16
	v_cmp_lt_i32_e64 s[36:37], v130, 17
	v_cmp_lt_i32_e64 s[38:39], v130, 18
	v_cmp_lt_i32_e64 s[40:41], v130, 19
	v_cndmask_b32_e64 v192, v192, v131, s[34:35]
	v_cndmask_b32_e64 v193, v193, v131, s[36:37]
	v_cndmask_b32_e64 v194, v194, v131, s[38:39]
	v_cndmask_b32_e64 v195, v195, v131, s[40:41]
	v_cmp_lt_i32_e64 s[34:35], v130, 24
	v_cmp_lt_i32_e64 s[36:37], v130, 25
	v_cmp_lt_i32_e64 s[38:39], v130, 26
	v_cmp_lt_i32_e64 s[40:41], v130, 27
	v_cndmask_b32_e64 v196, v196, v131, s[34:35]
	v_cndmask_b32_e64 v197, v197, v131, s[36:37]
	v_cndmask_b32_e64 v198, v198, v131, s[38:39]
	v_cndmask_b32_e64 v199, v199, v131, s[40:41]
	v_max3_f32 v243, v243, v184, v185
	v_max3_f32 v243, v243, v186, v187
	v_max3_f32 v243, v243, v188, v189
	v_max3_f32 v243, v243, v190, v191
	v_max3_f32 v243, v243, v192, v193
	v_max3_f32 v243, v243, v194, v195
	v_max3_f32 v243, v243, v196, v197
	v_max3_f32 v243, v243, v198, v199
	v_mov_b32_e32 v249, v243
	s_nop 1
	v_permlane32_swap_b32_e32 v243, v249
	s_waitcnt vmcnt(28)
	v_max3_f32 v246, v244, v243, v249
	v_sub_f32_e32 v247, v244, v246
	v_exp_f32_e32 v247, v247
	v_mov_b32_e32 v248, 0
	s_cmp_gt_u32 s9, 0
	s_cbranch_scc1 .Ldil_p1L0_eskip0
	v_sub_f32_e32 v80, v80, v246
	v_sub_f32_e32 v81, v81, v246
	v_exp_f32_e32 v80, v80
	v_sub_f32_e32 v82, v82, v246
	v_exp_f32_e32 v81, v81
	v_add_f32_e32 v248, v248, v80
	v_sub_f32_e32 v83, v83, v246
	v_exp_f32_e32 v82, v82
	v_add_f32_e32 v248, v248, v81
	v_sub_f32_e32 v84, v84, v246
	v_exp_f32_e32 v83, v83
	v_add_f32_e32 v248, v248, v82
	v_sub_f32_e32 v85, v85, v246
	v_exp_f32_e32 v84, v84
	v_add_f32_e32 v248, v248, v83
	v_sub_f32_e32 v86, v86, v246
	v_exp_f32_e32 v85, v85
	v_add_f32_e32 v248, v248, v84
	v_sub_f32_e32 v87, v87, v246
	v_exp_f32_e32 v86, v86
	v_add_f32_e32 v248, v248, v85
	v_sub_f32_e32 v88, v88, v246
	v_exp_f32_e32 v87, v87
	v_add_f32_e32 v248, v248, v86
	v_sub_f32_e32 v89, v89, v246
	v_exp_f32_e32 v88, v88
	v_add_f32_e32 v248, v248, v87
	v_sub_f32_e32 v90, v90, v246
	v_exp_f32_e32 v89, v89
	v_add_f32_e32 v248, v248, v88
	v_sub_f32_e32 v91, v91, v246
	v_exp_f32_e32 v90, v90
	v_add_f32_e32 v248, v248, v89
	v_sub_f32_e32 v92, v92, v246
	v_exp_f32_e32 v91, v91
	v_add_f32_e32 v248, v248, v90
	v_sub_f32_e32 v93, v93, v246
	v_exp_f32_e32 v92, v92
	v_add_f32_e32 v248, v248, v91
	v_sub_f32_e32 v94, v94, v246
	v_exp_f32_e32 v93, v93
	v_add_f32_e32 v248, v248, v92
	v_sub_f32_e32 v95, v95, v246
	v_exp_f32_e32 v94, v94
	v_add_f32_e32 v248, v248, v93
	v_exp_f32_e32 v95, v95
	v_add_f32_e32 v248, v248, v94
	s_nop 0
	v_add_f32_e32 v248, v248, v95

.Ldil_p1L0_eskip3:
	v_sub_f32_e32 v184, v184, v246
	v_sub_f32_e32 v185, v185, v246
	v_exp_f32_e32 v184, v184
	v_sub_f32_e32 v186, v186, v246
	v_exp_f32_e32 v185, v185
	v_add_f32_e32 v248, v248, v184
	v_sub_f32_e32 v187, v187, v246
	v_exp_f32_e32 v186, v186
	v_add_f32_e32 v248, v248, v185
	v_sub_f32_e32 v188, v188, v246
	v_exp_f32_e32 v187, v187
	v_add_f32_e32 v248, v248, v186
	v_sub_f32_e32 v189, v189, v246
	v_exp_f32_e32 v188, v188
	v_add_f32_e32 v248, v248, v187
	v_sub_f32_e32 v190, v190, v246
	v_exp_f32_e32 v189, v189
	v_add_f32_e32 v248, v248, v188
	v_sub_f32_e32 v191, v191, v246
	v_exp_f32_e32 v190, v190
	v_add_f32_e32 v248, v248, v189
	v_sub_f32_e32 v192, v192, v246
	v_exp_f32_e32 v191, v191
	v_add_f32_e32 v248, v248, v190
	v_sub_f32_e32 v193, v193, v246
	v_exp_f32_e32 v192, v192
	v_add_f32_e32 v248, v248, v191
	v_sub_f32_e32 v194, v194, v246
	v_exp_f32_e32 v193, v193
	v_add_f32_e32 v248, v248, v192
	v_sub_f32_e32 v195, v195, v246
	v_exp_f32_e32 v194, v194
	v_add_f32_e32 v248, v248, v193
	v_sub_f32_e32 v196, v196, v246
	v_exp_f32_e32 v195, v195
	v_add_f32_e32 v248, v248, v194
	v_sub_f32_e32 v197, v197, v246
	v_exp_f32_e32 v196, v196
	v_add_f32_e32 v248, v248, v195
	v_sub_f32_e32 v198, v198, v246
	v_exp_f32_e32 v197, v197
	v_add_f32_e32 v248, v248, v196
	v_sub_f32_e32 v199, v199, v246
	v_exp_f32_e32 v198, v198
	v_add_f32_e32 v248, v248, v197
	v_exp_f32_e32 v199, v199
	v_add_f32_e32 v248, v248, v198
	s_nop 0
	v_add_f32_e32 v248, v248, v199
	v_mov_b32_e32 v249, v248
	s_nop 1
	v_permlane32_swap_b32_e32 v248, v249
	s_nop 1
	v_add_f32_e32 v248, v248, v249
	v_fmac_f32_e32 v248, v245, v247
	s_waitcnt vmcnt(20)
	ds_write_b128 v204, v[208:211]
	ds_write_b128 v204, v[212:215] offset:1088
	ds_write_b128 v204, v[216:219] offset:2176
	ds_write_b128 v204, v[220:223] offset:3264
	ds_write_b128 v204, v[224:227] offset:4352
	ds_write_b128 v204, v[228:231] offset:5440
	ds_write_b128 v204, v[232:235] offset:6528
	ds_write_b128 v204, v[236:239] offset:7616
	s_waitcnt lgkmcnt(0)
	ds_read_b128 v[208:211], v205
	ds_read_b128 v[212:215], v205 offset:32
	ds_read_b128 v[216:219], v205 offset:64
	ds_read_b128 v[220:223], v205 offset:96
	ds_read_b128 v[224:227], v205 offset:128
	ds_read_b128 v[228:231], v205 offset:160
	ds_read_b128 v[232:235], v205 offset:192
	ds_read_b128 v[236:239], v205 offset:224
	s_waitcnt lgkmcnt(0)
	v_mul_f32_e32 v208, v208, v247
	v_mul_f32_e32 v224, v224, v247
	v_mul_f32_e32 v209, v209, v247
	v_mul_f32_e32 v225, v225, v247
	v_mul_f32_e32 v210, v210, v247
	v_mul_f32_e32 v226, v226, v247
	v_mul_f32_e32 v211, v211, v247
	v_mul_f32_e32 v227, v227, v247
	v_mul_f32_e32 v212, v212, v247
	v_mul_f32_e32 v228, v228, v247
	v_mul_f32_e32 v213, v213, v247
	v_mul_f32_e32 v229, v229, v247
	v_mul_f32_e32 v214, v214, v247
	v_mul_f32_e32 v230, v230, v247
	v_mul_f32_e32 v215, v215, v247
	v_mul_f32_e32 v231, v231, v247
	v_mul_f32_e32 v216, v216, v247
	v_mul_f32_e32 v232, v232, v247
	v_mul_f32_e32 v217, v217, v247
	v_mul_f32_e32 v233, v233, v247
	v_mul_f32_e32 v218, v218, v247
	v_mul_f32_e32 v234, v234, v247
	v_mul_f32_e32 v219, v219, v247
	v_mul_f32_e32 v235, v235, v247
	v_mul_f32_e32 v220, v220, v247
	v_mul_f32_e32 v236, v236, v247
	v_mul_f32_e32 v221, v221, v247
	v_mul_f32_e32 v237, v237, v247
	v_mul_f32_e32 v222, v222, v247
	v_mul_f32_e32 v238, v238, v247
	v_mul_f32_e32 v223, v223, v247
	v_mul_f32_e32 v239, v239, v247
	v_add_u32_e32 v251, 2304, v201
	s_cmp_gt_u32 s9, 0
	s_cbranch_scc1 .Ldil_p1L0_pskip0
	s_waitcnt vmcnt(16)
	ds_write_b16 v200, v0
	ds_write_b16_d16_hi v200, v0 offset:72
	ds_write_b16 v200, v1 offset:144
	ds_write_b16_d16_hi v200, v1 offset:216
	ds_write_b16 v200, v2 offset:288
	ds_write_b16_d16_hi v200, v2 offset:360
	ds_write_b16 v200, v3 offset:432
	ds_write_b16_d16_hi v200, v3 offset:504
	ds_write_b16 v200, v4 offset:16
	ds_write_b16_d16_hi v200, v4 offset:88
	ds_write_b16 v200, v5 offset:160
	ds_write_b16_d16_hi v200, v5 offset:232
	ds_write_b16 v200, v6 offset:304
	ds_write_b16_d16_hi v200, v6 offset:376
	ds_write_b16 v200, v7 offset:448
	ds_write_b16_d16_hi v200, v7 offset:520
	ds_write_b16 v200, v8 offset:32
	ds_write_b16_d16_hi v200, v8 offset:104
	ds_write_b16 v200, v9 offset:176
	ds_write_b16_d16_hi v200, v9 offset:248
	ds_write_b16 v200, v10 offset:320
	ds_write_b16_d16_hi v200, v10 offset:392
	ds_write_b16 v200, v11 offset:464
	ds_write_b16_d16_hi v200, v11 offset:536
	ds_write_b16 v200, v12 offset:48
	ds_write_b16_d16_hi v200, v12 offset:120
	ds_write_b16 v200, v13 offset:192
	ds_write_b16_d16_hi v200, v13 offset:264
	ds_write_b16 v200, v14 offset:336
	ds_write_b16_d16_hi v200, v14 offset:408
	ds_write_b16 v200, v15 offset:480
	ds_write_b16_d16_hi v200, v15 offset:552
	v_cvt_pk_bf16_f32 v136, v80, v81
	v_cvt_pk_bf16_f32 v137, v82, v83
	v_cvt_pk_bf16_f32 v138, v84, v85
	v_cvt_pk_bf16_f32 v139, v86, v87
	v_cvt_pk_bf16_f32 v140, v88, v89
	v_cvt_pk_bf16_f32 v141, v90, v91
	v_cvt_pk_bf16_f32 v142, v92, v93
	v_cvt_pk_bf16_f32 v143, v94, v95
	s_waitcnt lgkmcnt(0)
	ds_read2_b64 v[152:155], v201 offset0:0 offset1:2
	ds_read2_b64 v[156:159], v251 offset0:0 offset1:2
	ds_read2_b64 v[160:163], v201 offset0:4 offset1:6
	ds_read2_b64 v[164:167], v251 offset0:4 offset1:6
	s_waitcnt lgkmcnt(0)
	v_mfma_f32_32x32x16_bf16 v[208:223], v[152:155], v[136:139], v[208:223]
	v_mfma_f32_32x32x16_bf16 v[224:239], v[156:159], v[136:139], v[224:239]
	v_mfma_f32_32x32x16_bf16 v[208:223], v[160:163], v[140:143], v[208:223]
	v_mfma_f32_32x32x16_bf16 v[224:239], v[164:167], v[140:143], v[224:239]

.Ldil_p1L0_pskip3:
	s_waitcnt vmcnt(0)
	ds_write_b16 v200, v64
	ds_write_b16_d16_hi v200, v64 offset:72
	ds_write_b16 v200, v65 offset:144
	ds_write_b16_d16_hi v200, v65 offset:216
	ds_write_b16 v200, v66 offset:288
	ds_write_b16_d16_hi v200, v66 offset:360
	ds_write_b16 v200, v67 offset:432
	ds_write_b16_d16_hi v200, v67 offset:504
	ds_write_b16 v200, v68 offset:16
	ds_write_b16_d16_hi v200, v68 offset:88
	ds_write_b16 v200, v69 offset:160
	ds_write_b16_d16_hi v200, v69 offset:232
	ds_write_b16 v200, v70 offset:304
	ds_write_b16_d16_hi v200, v70 offset:376
	ds_write_b16 v200, v71 offset:448
	ds_write_b16_d16_hi v200, v71 offset:520
	ds_write_b16 v200, v72 offset:32
	ds_write_b16_d16_hi v200, v72 offset:104
	ds_write_b16 v200, v73 offset:176
	ds_write_b16_d16_hi v200, v73 offset:248
	ds_write_b16 v200, v74 offset:320
	ds_write_b16_d16_hi v200, v74 offset:392
	ds_write_b16 v200, v75 offset:464
	ds_write_b16_d16_hi v200, v75 offset:536
	ds_write_b16 v200, v76 offset:48
	ds_write_b16_d16_hi v200, v76 offset:120
	ds_write_b16 v200, v77 offset:192
	ds_write_b16_d16_hi v200, v77 offset:264
	ds_write_b16 v200, v78 offset:336
	ds_write_b16_d16_hi v200, v78 offset:408
	ds_write_b16 v200, v79 offset:480
	ds_write_b16_d16_hi v200, v79 offset:552
	v_cvt_pk_bf16_f32 v136, v184, v185
	v_cvt_pk_bf16_f32 v137, v186, v187
	v_cvt_pk_bf16_f32 v138, v188, v189
	v_cvt_pk_bf16_f32 v139, v190, v191
	v_cvt_pk_bf16_f32 v140, v192, v193
	v_cvt_pk_bf16_f32 v141, v194, v195
	v_cvt_pk_bf16_f32 v142, v196, v197
	v_cvt_pk_bf16_f32 v143, v198, v199
	s_waitcnt lgkmcnt(0)
	ds_read2_b64 v[152:155], v201 offset0:0 offset1:2
	ds_read2_b64 v[156:159], v251 offset0:0 offset1:2
	ds_read2_b64 v[160:163], v201 offset0:4 offset1:6
	ds_read2_b64 v[164:167], v251 offset0:4 offset1:6
	s_waitcnt lgkmcnt(0)
	v_mfma_f32_32x32x16_bf16 v[208:223], v[152:155], v[136:139], v[208:223]
	v_mfma_f32_32x32x16_bf16 v[224:239], v[156:159], v[136:139], v[224:239]
	v_mfma_f32_32x32x16_bf16 v[208:223], v[160:163], v[140:143], v[208:223]
	v_mfma_f32_32x32x16_bf16 v[224:239], v[164:167], v[140:143], v[224:239]
	s_nop 7
	s_nop 3
	ds_write_b128 v205, v[208:211]
	ds_write_b128 v205, v[212:215] offset:32
	ds_write_b128 v205, v[216:219] offset:64
	ds_write_b128 v205, v[220:223] offset:96
	ds_write_b128 v205, v[224:227] offset:128
	ds_write_b128 v205, v[228:231] offset:160
	ds_write_b128 v205, v[232:235] offset:192
	ds_write_b128 v205, v[236:239] offset:224
	s_waitcnt lgkmcnt(0)
	ds_read_b128 v[208:211], v204
	ds_read_b128 v[212:215], v204 offset:1088
	ds_read_b128 v[216:219], v204 offset:2176
	ds_read_b128 v[220:223], v204 offset:3264
	ds_read_b128 v[224:227], v204 offset:4352
	ds_read_b128 v[228:231], v204 offset:5440
	ds_read_b128 v[232:235], v204 offset:6528
	ds_read_b128 v[236:239], v204 offset:7616
	s_waitcnt lgkmcnt(0)
	global_store_dwordx4 v241, v[208:211], s[56:57]
	v_add_u32_e32 v252, 0x8000, v241
	global_store_dwordx4 v252, v[212:215], s[56:57]
	v_add_u32_e32 v252, 0x10000, v241
	global_store_dwordx4 v252, v[216:219], s[56:57]
	v_add_u32_e32 v252, 0x18000, v241
	global_store_dwordx4 v252, v[220:223], s[56:57]
	v_add_u32_e32 v252, 0x20000, v241
	global_store_dwordx4 v252, v[224:227], s[56:57]
	v_add_u32_e32 v252, 0x28000, v241
	global_store_dwordx4 v252, v[228:231], s[56:57]
	v_add_u32_e32 v252, 0x30000, v241
	global_store_dwordx4 v252, v[232:235], s[56:57]
	v_add_u32_e32 v252, 0x38000, v241
	global_store_dwordx4 v252, v[236:239], s[56:57]
	s_mov_b64 exec, 0xffffffff
	global_store_dword v240, v246, s[58:59]
	global_store_dword v240, v248, s[60:61]
	s_mov_b64 exec, -1
	s_lshl_b32 s99, s33, 3
	s_add_i32 s98, s98, s99
	s_cmpk_lt_i32 s98, 0x2000
	s_cbranch_scc1 .Ldil_p1L0_loop
	s_waitcnt lgkmcnt(0)
	s_branch .LBB0_443

.LBB0_499:
	s_mov_b64 exec, -1
	s_load_dwordx2 s[100:101], s[0:1], 0xf0
	s_mov_b32 s98, s8
	v_and_b32_e32 v128, 31, v206
	v_bfe_u32 v249, v206, 5, 1
	v_lshlrev_b32_e32 v129, 4, v249
	v_lshlrev_b32_e32 v250, 2, v249
	v_sub_u32_e32 v130, v128, v250
	v_mov_b32_e32 v131, 0xf149f2ca
	v_and_b32_e32 v133, 7, v206
	v_lshlrev_b32_e32 v133, 4, v133
	v_and_b32_e32 v134, 15, v206
	v_lshlrev_b32_e32 v134, 4, v134
	v_lshrrev_b32_e32 v251, 6, v206
	v_lshlrev_b32_e32 v251, 14, v251
	v_and_b32_e32 v252, 7, v206
	v_mul_u32_u24_e32 v252, 0x240, v252
	v_bfe_u32 v200, v206, 3, 3
	v_lshl_add_u32 v200, v200, 1, v252
	v_add_u32_e32 v200, v200, v251
	v_mul_u32_u24_e32 v252, 72, v128
	v_lshl_add_u32 v201, v249, 3, v252
	v_add_u32_e32 v201, v201, v251
	v_bfe_u32 v252, v206, 3, 3
	v_mul_u32_u24_e32 v252, 144, v252
	v_add3_u32 v202, v252, v133, v251
	v_add_u32_e32 v202, 4608, v202
	v_mul_u32_u24_e32 v252, 144, v128
	v_add3_u32 v203, v252, v129, v251
	v_add_u32_e32 v203, 4608, v203
	v_bfe_u32 v252, v206, 4, 2
	v_mul_u32_u24_e32 v252, 272, v252
	v_add3_u32 v204, v252, v134, v251
	v_add_u32_e32 v204, 4608, v204
	v_mul_u32_u24_e32 v252, 272, v128
	v_add3_u32 v205, v252, v129, v251
	v_add_u32_e32 v205, 4608, v205
	s_waitcnt lgkmcnt(0)
.Ldil_p2L0_loop:
	s_and_b32 s4, s98, 7
	s_bfe_u32 s5, s98, 0x40003
	s_lshr_b32 s6, s98, 10
	s_and_b32 s7, s98, 0x380
	s_lshl_b32 s99, s6, 12
	s_add_u32 s8, s99, s5
	s_sub_u32 s9, 4, s4
	s_max_i32 s9, s9, 0
	s_lshl_b32 s4, s4, 5
	v_add_u32_e32 v135, s4, v128
	s_lshl_b32 s99, s8, 10
	s_add_u32 s99, s99, s7
	s_add_u32 s64, s99, 0x16000000
	s_add_u32 s64, s100, s64
	s_addc_u32 s65, s101, 0
	s_add_u32 s72, s64, 0x2000000
	s_addc_u32 s73, s65, 0
	s_add_u32 s52, s72, 0x2000000
	s_addc_u32 s53, s73, 0
	s_mov_b64 s[80:81], s[52:53]
	s_add_u32 s82, s80, 0x20000
	s_addc_u32 s83, s81, 0
	s_add_u32 s84, s82, 0x20000
	s_addc_u32 s85, s83, 0
	s_add_u32 s86, s84, 0x20000
	s_addc_u32 s87, s85, 0
	s_add_u32 s66, s64, 0x20000
	s_addc_u32 s67, s65, 0
	s_add_u32 s74, s72, 0x20000
	s_addc_u32 s75, s73, 0
	s_add_u32 s68, s66, 0x20000
	s_addc_u32 s69, s67, 0
	s_add_u32 s76, s74, 0x20000
	s_addc_u32 s77, s75, 0
	s_add_u32 s70, s68, 0x20000
	s_addc_u32 s71, s69, 0
	s_add_u32 s78, s76, 0x20000
	s_addc_u32 s79, s77, 0
	v_bfe_u32 v249, v206, 3, 3
	v_add_u32_e32 v249, s4, v249
	v_mov_b32_e32 v253, v249
	v_lshl_add_u32 v250, v249, 14, v133
	global_load_dwordx4 v[152:155], v250, s[64:65]
	global_load_dwordx4 v[156:159], v250, s[66:67]
	global_load_dwordx4 v[160:163], v250, s[68:69]
	global_load_dwordx4 v[164:167], v250, s[70:71]
	s_max_u32 s99, s9, 0
	s_lshl_b32 s99, s99, 5
	s_addk_i32 s99, 0xff80
	v_add_u32_e32 v250, s99, v249
	v_lshl_add_u32 v250, v250, 14, v133
	global_load_dwordx4 v[0:3], v250, s[72:73]
	global_load_dwordx4 v[4:7], v250, s[74:75]
	global_load_dwordx4 v[8:11], v250, s[76:77]
	global_load_dwordx4 v[12:15], v250, s[78:79]
	s_max_u32 s99, s9, 1
	s_lshl_b32 s99, s99, 5
	s_addk_i32 s99, 0xff80
	v_add_u32_e32 v250, s99, v249
	v_lshl_add_u32 v250, v250, 14, v133
	global_load_dwordx4 v[16:19], v250, s[72:73]
	global_load_dwordx4 v[20:23], v250, s[74:75]
	global_load_dwordx4 v[24:27], v250, s[76:77]
	global_load_dwordx4 v[28:31], v250, s[78:79]
	s_max_u32 s99, s9, 2
	s_lshl_b32 s99, s99, 5
	s_addk_i32 s99, 0xff80
	v_add_u32_e32 v250, s99, v249
	v_lshl_add_u32 v250, v250, 14, v133
	global_load_dwordx4 v[32:35], v250, s[72:73]
	global_load_dwordx4 v[36:39], v250, s[74:75]
	global_load_dwordx4 v[40:43], v250, s[76:77]
	global_load_dwordx4 v[44:47], v250, s[78:79]
	s_max_u32 s99, s9, 3
	s_lshl_b32 s99, s99, 5
	s_addk_i32 s99, 0xff80
	v_add_u32_e32 v250, s99, v249
	v_lshl_add_u32 v250, v250, 14, v133
	global_load_dwordx4 v[48:51], v250, s[72:73]
	global_load_dwordx4 v[52:55], v250, s[74:75]
	global_load_dwordx4 v[56:59], v250, s[76:77]
	global_load_dwordx4 v[60:63], v250, s[78:79]
	s_max_u32 s99, s9, 4
	s_lshl_b32 s99, s99, 5
	s_addk_i32 s99, 0xff80
	v_add_u32_e32 v250, s99, v249
	v_lshl_add_u32 v250, v250, 14, v133
	global_load_dwordx4 v[64:67], v250, s[72:73]
	global_load_dwordx4 v[68:71], v250, s[74:75]
	global_load_dwordx4 v[72:75], v250, s[76:77]
	global_load_dwordx4 v[76:79], v250, s[78:79]
	s_lshl_b32 s99, s8, 5
	s_lshr_b32 s58, s7, 5
	s_add_u32 s99, s99, s58
	s_add_u32 s99, s99, 0x400000
	s_add_u32 s58, s100, s99
	s_addc_u32 s59, s101, 0
	s_add_u32 s60, s58, 0x100000
	s_addc_u32 s61, s59, 0
	v_lshlrev_b32_e32 v240, 9, v135
	s_lshl_b32 s99, s8, 11
	s_lshl_b32 s56, s7, 1
	s_add_u32 s99, s99, s56
	s_add_u32 s99, s99, 0x8000000
	s_add_u32 s56, s100, s99
	s_addc_u32 s57, s101, 0
	v_bfe_u32 v251, v206, 4, 2
	v_add_u32_e32 v251, s4, v251
	v_lshl_add_u32 v241, v251, 15, v134
	global_load_dword v244, v240, s[58:59]
	global_load_dword v245, v240, s[60:61]
	global_load_dwordx4 v[208:211], v241, s[56:57]
	v_add_u32_e32 v252, 0x20000, v241
	global_load_dwordx4 v[212:215], v252, s[56:57]
	v_add_u32_e32 v252, 0x40000, v241
	global_load_dwordx4 v[216:219], v252, s[56:57]
	v_add_u32_e32 v252, 0x60000, v241
	global_load_dwordx4 v[220:223], v252, s[56:57]
	v_add_u32_e32 v252, 0x80000, v241
	global_load_dwordx4 v[224:227], v252, s[56:57]
	v_add_u32_e32 v252, 0xa0000, v241
	global_load_dwordx4 v[228:231], v252, s[56:57]
	v_add_u32_e32 v252, 0xc0000, v241
	global_load_dwordx4 v[232:235], v252, s[56:57]
	v_add_u32_e32 v252, 0xe0000, v241
	global_load_dwordx4 v[236:239], v252, s[56:57]
	s_lshl_b32 s99, s8, 11
	s_add_u32 s99, s99, s7
	s_add_u32 s99, s99, 0xc000400
	s_add_u32 s62, s100, s99
	s_addc_u32 s63, s101, 0
	v_lshl_add_u32 v242, v249, 15, v133
	v_mov_b32_e32 v243, v131
	s_waitcnt vmcnt(30)
	ds_write_b128 v202, v[152:155]
	ds_write_b128 v202, v[156:159] offset:1152
	ds_write_b128 v202, v[160:163] offset:2304
	ds_write_b128 v202, v[164:167] offset:3456
	s_waitcnt lgkmcnt(0)
	ds_read_b128 v[136:139], v203
	ds_read_b128 v[140:143], v203 offset:32
	ds_read_b128 v[144:147], v203 offset:64
	ds_read_b128 v[148:151], v203 offset:96
	s_cmp_gt_u32 s9, 0
	s_cbranch_scc1 .Ldil_p2L0_kskip0
	s_waitcnt vmcnt(26)
	s_waitcnt lgkmcnt(0)
	ds_write_b128 v202, v[0:3]
	ds_write_b128 v202, v[4:7] offset:1152
	ds_write_b128 v202, v[8:11] offset:2304
	ds_write_b128 v202, v[12:15] offset:3456
	s_waitcnt lgkmcnt(0)
	s_max_u32 s99, s9, 0
	s_lshl_b32 s99, s99, 5
	s_addk_i32 s99, 0xff80
	v_add_u32_e32 v250, s99, v253
	v_lshl_add_u32 v250, v250, 14, v133
	global_load_dwordx4 v[0:3], v250, s[80:81]
	global_load_dwordx4 v[4:7], v250, s[82:83]
	global_load_dwordx4 v[8:11], v250, s[84:85]
	global_load_dwordx4 v[12:15], v250, s[86:87]
	ds_read_b128 v[152:155], v203
	ds_read_b128 v[156:159], v203 offset:32
	ds_read_b128 v[160:163], v203 offset:64
	ds_read_b128 v[164:167], v203 offset:96
	s_waitcnt lgkmcnt(0)
	v_mfma_f32_32x32x16_bf16 v[80:95], v[152:155], v[136:139], 0
	v_mfma_f32_32x32x16_bf16 v[80:95], v[156:159], v[140:143], v[80:95]
	v_mfma_f32_32x32x16_bf16 v[80:95], v[160:163], v[144:147], v[80:95]
	v_mfma_f32_32x32x16_bf16 v[80:95], v[164:167], v[148:151], v[80:95]
	s_nop 7
	s_nop 3
	v_cmp_gt_i32_e64 s[34:35], v130, 0
	v_cmp_gt_i32_e64 s[36:37], v130, 1
	v_cmp_gt_i32_e64 s[38:39], v130, 2
	v_cmp_gt_i32_e64 s[40:41], v130, 3
	v_cndmask_b32_e64 v80, v80, v131, s[34:35]
	v_cndmask_b32_e64 v81, v81, v131, s[36:37]
	v_cndmask_b32_e64 v82, v82, v131, s[38:39]
	v_cndmask_b32_e64 v83, v83, v131, s[40:41]
	v_cmp_gt_i32_e64 s[34:35], v130, 8
	v_cmp_gt_i32_e64 s[36:37], v130, 9
	v_cmp_gt_i32_e64 s[38:39], v130, 10
	v_cmp_gt_i32_e64 s[40:41], v130, 11
	v_cndmask_b32_e64 v84, v84, v131, s[34:35]
	v_cndmask_b32_e64 v85, v85, v131, s[36:37]
	v_cndmask_b32_e64 v86, v86, v131, s[38:39]
	v_cndmask_b32_e64 v87, v87, v131, s[40:41]
	v_cmp_gt_i32_e64 s[34:35], v130, 16
	v_cmp_gt_i32_e64 s[36:37], v130, 17
	v_cmp_gt_i32_e64 s[38:39], v130, 18
	v_cmp_gt_i32_e64 s[40:41], v130, 19
	v_cndmask_b32_e64 v88, v88, v131, s[34:35]
	v_cndmask_b32_e64 v89, v89, v131, s[36:37]
	v_cndmask_b32_e64 v90, v90, v131, s[38:39]
	v_cndmask_b32_e64 v91, v91, v131, s[40:41]
	v_cmp_gt_i32_e64 s[34:35], v130, 24
	v_cmp_gt_i32_e64 s[36:37], v130, 25
	v_cmp_gt_i32_e64 s[38:39], v130, 26
	v_cmp_gt_i32_e64 s[40:41], v130, 27
	v_cndmask_b32_e64 v92, v92, v131, s[34:35]
	v_cndmask_b32_e64 v93, v93, v131, s[36:37]
	v_cndmask_b32_e64 v94, v94, v131, s[38:39]
	v_cndmask_b32_e64 v95, v95, v131, s[40:41]
	v_max3_f32 v243, v243, v80, v81
	v_max3_f32 v243, v243, v82, v83
	v_max3_f32 v243, v243, v84, v85
	v_max3_f32 v243, v243, v86, v87
	v_max3_f32 v243, v243, v88, v89
	v_max3_f32 v243, v243, v90, v91
	v_max3_f32 v243, v243, v92, v93
	v_max3_f32 v243, v243, v94, v95
	s_branch .Ldil_p2L0_kdone0
.Ldil_p2L0_kskip0:
	s_max_u32 s99, s9, 0
	s_lshl_b32 s99, s99, 5
	s_addk_i32 s99, 0xff80
	v_add_u32_e32 v250, s99, v253
	v_lshl_add_u32 v250, v250, 14, v133
	global_load_dwordx4 v[0:3], v250, s[80:81]
	global_load_dwordx4 v[4:7], v250, s[82:83]
	global_load_dwordx4 v[8:11], v250, s[84:85]
	global_load_dwordx4 v[12:15], v250, s[86:87]
.Ldil_p2L0_kdone0:
	s_cmp_gt_u32 s9, 1
	s_cbranch_scc1 .Ldil_p2L0_kskip1
	s_waitcnt vmcnt(26)
	s_waitcnt lgkmcnt(0)
	ds_write_b128 v202, v[16:19]
	ds_write_b128 v202, v[20:23] offset:1152
	ds_write_b128 v202, v[24:27] offset:2304
	ds_write_b128 v202, v[28:31] offset:3456
	s_waitcnt lgkmcnt(0)
	s_max_u32 s99, s9, 1
	s_lshl_b32 s99, s99, 5
	s_addk_i32 s99, 0xff80
	v_add_u32_e32 v250, s99, v253
	v_lshl_add_u32 v250, v250, 14, v133
	global_load_dwordx4 v[16:19], v250, s[80:81]
	global_load_dwordx4 v[20:23], v250, s[82:83]
	global_load_dwordx4 v[24:27], v250, s[84:85]
	global_load_dwordx4 v[28:31], v250, s[86:87]
	ds_read_b128 v[152:155], v203
	ds_read_b128 v[156:159], v203 offset:32
	ds_read_b128 v[160:163], v203 offset:64
	ds_read_b128 v[164:167], v203 offset:96
	s_waitcnt lgkmcnt(0)
	v_mfma_f32_32x32x16_bf16 v[96:111], v[152:155], v[136:139], 0
	v_mfma_f32_32x32x16_bf16 v[96:111], v[156:159], v[140:143], v[96:111]
	v_mfma_f32_32x32x16_bf16 v[96:111], v[160:163], v[144:147], v[96:111]
	v_mfma_f32_32x32x16_bf16 v[96:111], v[164:167], v[148:151], v[96:111]
	s_nop 7
	s_nop 3
	v_max3_f32 v243, v243, v96, v97
	v_max3_f32 v243, v243, v98, v99
	v_max3_f32 v243, v243, v100, v101
	v_max3_f32 v243, v243, v102, v103
	v_max3_f32 v243, v243, v104, v105
	v_max3_f32 v243, v243, v106, v107
	v_max3_f32 v243, v243, v108, v109
	v_max3_f32 v243, v243, v110, v111
	s_branch .Ldil_p2L0_kdone1
.Ldil_p2L0_kskip1:
	s_max_u32 s99, s9, 1
	s_lshl_b32 s99, s99, 5
	s_addk_i32 s99, 0xff80
	v_add_u32_e32 v250, s99, v253
	v_lshl_add_u32 v250, v250, 14, v133
	global_load_dwordx4 v[16:19], v250, s[80:81]
	global_load_dwordx4 v[20:23], v250, s[82:83]
	global_load_dwordx4 v[24:27], v250, s[84:85]
	global_load_dwordx4 v[28:31], v250, s[86:87]
.Ldil_p2L0_kdone1:
	s_cmp_gt_u32 s9, 2
	s_cbranch_scc1 .Ldil_p2L0_kskip2
	s_waitcnt vmcnt(26)
	s_waitcnt lgkmcnt(0)
	ds_write_b128 v202, v[32:35]
	ds_write_b128 v202, v[36:39] offset:1152
	ds_write_b128 v202, v[40:43] offset:2304
	ds_write_b128 v202, v[44:47] offset:3456
	s_waitcnt lgkmcnt(0)
	s_max_u32 s99, s9, 2
	s_lshl_b32 s99, s99, 5
	s_addk_i32 s99, 0xff80
	v_add_u32_e32 v250, s99, v253
	v_lshl_add_u32 v250, v250, 14, v133
	global_load_dwordx4 v[32:35], v250, s[80:81]
	global_load_dwordx4 v[36:39], v250, s[82:83]
	global_load_dwordx4 v[40:43], v250, s[84:85]
	global_load_dwordx4 v[44:47], v250, s[86:87]
	ds_read_b128 v[152:155], v203
	ds_read_b128 v[156:159], v203 offset:32
	ds_read_b128 v[160:163], v203 offset:64
	ds_read_b128 v[164:167], v203 offset:96
	s_waitcnt lgkmcnt(0)
	v_mfma_f32_32x32x16_bf16 v[112:127], v[152:155], v[136:139], 0
	v_mfma_f32_32x32x16_bf16 v[112:127], v[156:159], v[140:143], v[112:127]
	v_mfma_f32_32x32x16_bf16 v[112:127], v[160:163], v[144:147], v[112:127]
	v_mfma_f32_32x32x16_bf16 v[112:127], v[164:167], v[148:151], v[112:127]
	s_nop 7
	s_nop 3
	v_max3_f32 v243, v243, v112, v113
	v_max3_f32 v243, v243, v114, v115
	v_max3_f32 v243, v243, v116, v117
	v_max3_f32 v243, v243, v118, v119
	v_max3_f32 v243, v243, v120, v121
	v_max3_f32 v243, v243, v122, v123
	v_max3_f32 v243, v243, v124, v125
	v_max3_f32 v243, v243, v126, v127
	s_branch .Ldil_p2L0_kdone2
.Ldil_p2L0_kskip2:
	s_max_u32 s99, s9, 2
	s_lshl_b32 s99, s99, 5
	s_addk_i32 s99, 0xff80
	v_add_u32_e32 v250, s99, v253
	v_lshl_add_u32 v250, v250, 14, v133
	global_load_dwordx4 v[32:35], v250, s[80:81]
	global_load_dwordx4 v[36:39], v250, s[82:83]
	global_load_dwordx4 v[40:43], v250, s[84:85]
	global_load_dwordx4 v[44:47], v250, s[86:87]
.Ldil_p2L0_kdone2:
	s_cmp_gt_u32 s9, 3
	s_cbranch_scc1 .Ldil_p2L0_kskip3
	s_waitcnt vmcnt(26)
	s_waitcnt lgkmcnt(0)
	ds_write_b128 v202, v[48:51]
	ds_write_b128 v202, v[52:55] offset:1152
	ds_write_b128 v202, v[56:59] offset:2304
	ds_write_b128 v202, v[60:63] offset:3456
	s_waitcnt lgkmcnt(0)
	s_max_u32 s99, s9, 3
	s_lshl_b32 s99, s99, 5
	s_addk_i32 s99, 0xff80
	v_add_u32_e32 v250, s99, v253
	v_lshl_add_u32 v250, v250, 14, v133
	global_load_dwordx4 v[48:51], v250, s[80:81]
	global_load_dwordx4 v[52:55], v250, s[82:83]
	global_load_dwordx4 v[56:59], v250, s[84:85]
	global_load_dwordx4 v[60:63], v250, s[86:87]
	ds_read_b128 v[152:155], v203
	ds_read_b128 v[156:159], v203 offset:32
	ds_read_b128 v[160:163], v203 offset:64
	ds_read_b128 v[164:167], v203 offset:96
	s_waitcnt lgkmcnt(0)
	v_mfma_f32_32x32x16_bf16 v[168:183], v[152:155], v[136:139], 0
	v_mfma_f32_32x32x16_bf16 v[168:183], v[156:159], v[140:143], v[168:183]
	v_mfma_f32_32x32x16_bf16 v[168:183], v[160:163], v[144:147], v[168:183]
	v_mfma_f32_32x32x16_bf16 v[168:183], v[164:167], v[148:151], v[168:183]
	s_nop 7
	s_nop 3
	v_max3_f32 v243, v243, v168, v169
	v_max3_f32 v243, v243, v170, v171
	v_max3_f32 v243, v243, v172, v173
	v_max3_f32 v243, v243, v174, v175
	v_max3_f32 v243, v243, v176, v177
	v_max3_f32 v243, v243, v178, v179
	v_max3_f32 v243, v243, v180, v181
	v_max3_f32 v243, v243, v182, v183
	s_branch .Ldil_p2L0_kdone3
.Ldil_p2L0_kskip3:
	s_max_u32 s99, s9, 3
	s_lshl_b32 s99, s99, 5
	s_addk_i32 s99, 0xff80
	v_add_u32_e32 v250, s99, v253
	v_lshl_add_u32 v250, v250, 14, v133
	global_load_dwordx4 v[48:51], v250, s[80:81]
	global_load_dwordx4 v[52:55], v250, s[82:83]
	global_load_dwordx4 v[56:59], v250, s[84:85]
	global_load_dwordx4 v[60:63], v250, s[86:87]
.Ldil_p2L0_kdone3:
	s_waitcnt vmcnt(26)
	s_waitcnt lgkmcnt(0)
	ds_write_b128 v202, v[64:67]
	ds_write_b128 v202, v[68:71] offset:1152
	ds_write_b128 v202, v[72:75] offset:2304
	ds_write_b128 v202, v[76:79] offset:3456
	s_waitcnt lgkmcnt(0)
	s_max_u32 s99, s9, 4
	s_lshl_b32 s99, s99, 5
	s_addk_i32 s99, 0xff80
	v_add_u32_e32 v250, s99, v253
	v_lshl_add_u32 v250, v250, 14, v133
	global_load_dwordx4 v[64:67], v250, s[80:81]
	global_load_dwordx4 v[68:71], v250, s[82:83]
	global_load_dwordx4 v[72:75], v250, s[84:85]
	global_load_dwordx4 v[76:79], v250, s[86:87]
	ds_read_b128 v[152:155], v203
	ds_read_b128 v[156:159], v203 offset:32
	ds_read_b128 v[160:163], v203 offset:64
	ds_read_b128 v[164:167], v203 offset:96
	s_waitcnt lgkmcnt(0)
	v_mfma_f32_32x32x16_bf16 v[184:199], v[152:155], v[136:139], 0
	v_mfma_f32_32x32x16_bf16 v[184:199], v[156:159], v[140:143], v[184:199]
	v_mfma_f32_32x32x16_bf16 v[184:199], v[160:163], v[144:147], v[184:199]
	v_mfma_f32_32x32x16_bf16 v[184:199], v[164:167], v[148:151], v[184:199]
	s_nop 7
	s_nop 3
	v_cmp_lt_i32_e64 s[34:35], v130, 0
	v_cmp_lt_i32_e64 s[36:37], v130, 1
	v_cmp_lt_i32_e64 s[38:39], v130, 2
	v_cmp_lt_i32_e64 s[40:41], v130, 3
	v_cndmask_b32_e64 v184, v184, v131, s[34:35]
	v_cndmask_b32_e64 v185, v185, v131, s[36:37]
	v_cndmask_b32_e64 v186, v186, v131, s[38:39]
	v_cndmask_b32_e64 v187, v187, v131, s[40:41]
	v_cmp_lt_i32_e64 s[34:35], v130, 8
	v_cmp_lt_i32_e64 s[36:37], v130, 9
	v_cmp_lt_i32_e64 s[38:39], v130, 10
	v_cmp_lt_i32_e64 s[40:41], v130, 11
	v_cndmask_b32_e64 v188, v188, v131, s[34:35]
	v_cndmask_b32_e64 v189, v189, v131, s[36:37]
	v_cndmask_b32_e64 v190, v190, v131, s[38:39]
	v_cndmask_b32_e64 v191, v191, v131, s[40:41]
	v_cmp_lt_i32_e64 s[34:35], v130, 16
	v_cmp_lt_i32_e64 s[36:37], v130, 17
	v_cmp_lt_i32_e64 s[38:39], v130, 18
	v_cmp_lt_i32_e64 s[40:41], v130, 19
	v_cndmask_b32_e64 v192, v192, v131, s[34:35]
	v_cndmask_b32_e64 v193, v193, v131, s[36:37]
	v_cndmask_b32_e64 v194, v194, v131, s[38:39]
	v_cndmask_b32_e64 v195, v195, v131, s[40:41]
	v_cmp_lt_i32_e64 s[34:35], v130, 24
	v_cmp_lt_i32_e64 s[36:37], v130, 25
	v_cmp_lt_i32_e64 s[38:39], v130, 26
	v_cmp_lt_i32_e64 s[40:41], v130, 27
	v_cndmask_b32_e64 v196, v196, v131, s[34:35]
	v_cndmask_b32_e64 v197, v197, v131, s[36:37]
	v_cndmask_b32_e64 v198, v198, v131, s[38:39]
	v_cndmask_b32_e64 v199, v199, v131, s[40:41]
	v_max3_f32 v243, v243, v184, v185
	v_max3_f32 v243, v243, v186, v187
	v_max3_f32 v243, v243, v188, v189
	v_max3_f32 v243, v243, v190, v191
	v_max3_f32 v243, v243, v192, v193
	v_max3_f32 v243, v243, v194, v195
	v_max3_f32 v243, v243, v196, v197
	v_max3_f32 v243, v243, v198, v199
	v_mov_b32_e32 v249, v243
	s_nop 1
	v_permlane32_swap_b32_e32 v243, v249
	s_waitcnt vmcnt(28)
	v_max3_f32 v246, v244, v243, v249
	v_sub_f32_e32 v247, v244, v246
	v_exp_f32_e32 v247, v247
	v_mov_b32_e32 v248, 0
	s_cmp_gt_u32 s9, 0
	s_cbranch_scc1 .Ldil_p2L0_eskip0
	v_sub_f32_e32 v80, v80, v246
	v_sub_f32_e32 v81, v81, v246
	v_exp_f32_e32 v80, v80
	v_sub_f32_e32 v82, v82, v246
	v_exp_f32_e32 v81, v81
	v_add_f32_e32 v248, v248, v80
	v_sub_f32_e32 v83, v83, v246
	v_exp_f32_e32 v82, v82
	v_add_f32_e32 v248, v248, v81
	v_sub_f32_e32 v84, v84, v246
	v_exp_f32_e32 v83, v83
	v_add_f32_e32 v248, v248, v82
	v_sub_f32_e32 v85, v85, v246
	v_exp_f32_e32 v84, v84
	v_add_f32_e32 v248, v248, v83
	v_sub_f32_e32 v86, v86, v246
	v_exp_f32_e32 v85, v85
	v_add_f32_e32 v248, v248, v84
	v_sub_f32_e32 v87, v87, v246
	v_exp_f32_e32 v86, v86
	v_add_f32_e32 v248, v248, v85
	v_sub_f32_e32 v88, v88, v246
	v_exp_f32_e32 v87, v87
	v_add_f32_e32 v248, v248, v86
	v_sub_f32_e32 v89, v89, v246
	v_exp_f32_e32 v88, v88
	v_add_f32_e32 v248, v248, v87
	v_sub_f32_e32 v90, v90, v246
	v_exp_f32_e32 v89, v89
	v_add_f32_e32 v248, v248, v88
	v_sub_f32_e32 v91, v91, v246
	v_exp_f32_e32 v90, v90
	v_add_f32_e32 v248, v248, v89
	v_sub_f32_e32 v92, v92, v246
	v_exp_f32_e32 v91, v91
	v_add_f32_e32 v248, v248, v90
	v_sub_f32_e32 v93, v93, v246
	v_exp_f32_e32 v92, v92
	v_add_f32_e32 v248, v248, v91
	v_sub_f32_e32 v94, v94, v246
	v_exp_f32_e32 v93, v93
	v_add_f32_e32 v248, v248, v92
	v_sub_f32_e32 v95, v95, v246
	v_exp_f32_e32 v94, v94
	v_add_f32_e32 v248, v248, v93
	v_exp_f32_e32 v95, v95
	v_add_f32_e32 v248, v248, v94
	s_nop 0
	v_add_f32_e32 v248, v248, v95

.Ldil_p2L0_pskip3:
	s_waitcnt vmcnt(0)
	ds_write_b16 v200, v64
	ds_write_b16_d16_hi v200, v64 offset:72
	ds_write_b16 v200, v65 offset:144
	ds_write_b16_d16_hi v200, v65 offset:216
	ds_write_b16 v200, v66 offset:288
	ds_write_b16_d16_hi v200, v66 offset:360
	ds_write_b16 v200, v67 offset:432
	ds_write_b16_d16_hi v200, v67 offset:504
	ds_write_b16 v200, v68 offset:16
	ds_write_b16_d16_hi v200, v68 offset:88
	ds_write_b16 v200, v69 offset:160
	ds_write_b16_d16_hi v200, v69 offset:232
	ds_write_b16 v200, v70 offset:304
	ds_write_b16_d16_hi v200, v70 offset:376
	ds_write_b16 v200, v71 offset:448
	ds_write_b16_d16_hi v200, v71 offset:520
	ds_write_b16 v200, v72 offset:32
	ds_write_b16_d16_hi v200, v72 offset:104
	ds_write_b16 v200, v73 offset:176
	ds_write_b16_d16_hi v200, v73 offset:248
	ds_write_b16 v200, v74 offset:320
	ds_write_b16_d16_hi v200, v74 offset:392
	ds_write_b16 v200, v75 offset:464
	ds_write_b16_d16_hi v200, v75 offset:536
	ds_write_b16 v200, v76 offset:48
	ds_write_b16_d16_hi v200, v76 offset:120
	ds_write_b16 v200, v77 offset:192
	ds_write_b16_d16_hi v200, v77 offset:264
	ds_write_b16 v200, v78 offset:336
	ds_write_b16_d16_hi v200, v78 offset:408
	ds_write_b16 v200, v79 offset:480
	ds_write_b16_d16_hi v200, v79 offset:552
	v_cvt_pk_bf16_f32 v136, v184, v185
	v_cvt_pk_bf16_f32 v137, v186, v187
	v_cvt_pk_bf16_f32 v138, v188, v189
	v_cvt_pk_bf16_f32 v139, v190, v191
	v_cvt_pk_bf16_f32 v140, v192, v193
	v_cvt_pk_bf16_f32 v141, v194, v195
	v_cvt_pk_bf16_f32 v142, v196, v197
	v_cvt_pk_bf16_f32 v143, v198, v199
	s_waitcnt lgkmcnt(0)
	ds_read2_b64 v[152:155], v201 offset0:0 offset1:2
	ds_read2_b64 v[156:159], v251 offset0:0 offset1:2
	ds_read2_b64 v[160:163], v201 offset0:4 offset1:6
	ds_read2_b64 v[164:167], v251 offset0:4 offset1:6
	s_waitcnt lgkmcnt(0)
	v_mfma_f32_32x32x16_bf16 v[208:223], v[152:155], v[136:139], v[208:223]
	v_mfma_f32_32x32x16_bf16 v[224:239], v[156:159], v[136:139], v[224:239]
	v_mfma_f32_32x32x16_bf16 v[208:223], v[160:163], v[140:143], v[208:223]
	v_mfma_f32_32x32x16_bf16 v[224:239], v[164:167], v[140:143], v[224:239]
	v_rcp_f32_e32 v249, v248
	s_nop 0
	v_fma_f32 v250, -v248, v249, 1.0
	v_fmac_f32_e32 v249, v250, v249
	v_lshrrev_b32_e32 v252, 1, v129
	v_sub_u32_e32 v252, v203, v252
	s_nop 5
	v_mul_f32_e32 v208, v208, v249
	v_mul_f32_e32 v209, v209, v249
	v_mul_f32_e32 v210, v210, v249
	v_mul_f32_e32 v211, v211, v249
	v_cvt_pk_bf16_f32 v208, v208, v209
	v_cvt_pk_bf16_f32 v209, v210, v211
	ds_write_b64 v252, v[208:209]
	v_mul_f32_e32 v212, v212, v249
	v_mul_f32_e32 v213, v213, v249
	v_mul_f32_e32 v214, v214, v249
	v_mul_f32_e32 v215, v215, v249
	v_cvt_pk_bf16_f32 v212, v212, v213
	v_cvt_pk_bf16_f32 v213, v214, v215
	ds_write_b64 v252, v[212:213] offset:16
	v_mul_f32_e32 v216, v216, v249
	v_mul_f32_e32 v217, v217, v249
	v_mul_f32_e32 v218, v218, v249
	v_mul_f32_e32 v219, v219, v249
	v_cvt_pk_bf16_f32 v216, v216, v217
	v_cvt_pk_bf16_f32 v217, v218, v219
	ds_write_b64 v252, v[216:217] offset:32
	v_mul_f32_e32 v220, v220, v249
	v_mul_f32_e32 v221, v221, v249
	v_mul_f32_e32 v222, v222, v249
	v_mul_f32_e32 v223, v223, v249
	v_cvt_pk_bf16_f32 v220, v220, v221
	v_cvt_pk_bf16_f32 v221, v222, v223
	ds_write_b64 v252, v[220:221] offset:48
	v_mul_f32_e32 v224, v224, v249
	v_mul_f32_e32 v225, v225, v249
	v_mul_f32_e32 v226, v226, v249
	v_mul_f32_e32 v227, v227, v249
	v_cvt_pk_bf16_f32 v224, v224, v225
	v_cvt_pk_bf16_f32 v225, v226, v227
	ds_write_b64 v252, v[224:225] offset:64
	v_mul_f32_e32 v228, v228, v249
	v_mul_f32_e32 v229, v229, v249
	v_mul_f32_e32 v230, v230, v249
	v_mul_f32_e32 v231, v231, v249
	v_cvt_pk_bf16_f32 v228, v228, v229
	v_cvt_pk_bf16_f32 v229, v230, v231
	ds_write_b64 v252, v[228:229] offset:80
	v_mul_f32_e32 v232, v232, v249
	v_mul_f32_e32 v233, v233, v249
	v_mul_f32_e32 v234, v234, v249
	v_mul_f32_e32 v235, v235, v249
	v_cvt_pk_bf16_f32 v232, v232, v233
	v_cvt_pk_bf16_f32 v233, v234, v235
	ds_write_b64 v252, v[232:233] offset:96
	v_mul_f32_e32 v236, v236, v249
	v_mul_f32_e32 v237, v237, v249
	v_mul_f32_e32 v238, v238, v249
	v_mul_f32_e32 v239, v239, v249
	v_cvt_pk_bf16_f32 v236, v236, v237
	v_cvt_pk_bf16_f32 v237, v238, v239
	ds_write_b64 v252, v[236:237] offset:112
	s_waitcnt lgkmcnt(0)
	ds_read_b128 v[208:211], v202
	ds_read_b128 v[212:215], v202 offset:1152
	ds_read_b128 v[216:219], v202 offset:2304
	ds_read_b128 v[220:223], v202 offset:3456
	s_waitcnt lgkmcnt(0)
	global_store_dwordx4 v242, v[208:211], s[62:63]
	v_add_u32_e32 v250, 0x40000, v242
	global_store_dwordx4 v250, v[212:215], s[62:63]
	v_add_u32_e32 v250, 0x80000, v242
	global_store_dwordx4 v250, v[216:219], s[62:63]
	v_add_u32_e32 v250, 0xc0000, v242
	global_store_dwordx4 v250, v[220:223], s[62:63]
	s_lshl_b32 s99, s33, 3
	s_add_i32 s98, s98, s99
	s_cmpk_lt_i32 s98, 0x2000
	s_cbranch_scc1 .Ldil_p2L0_loop
	s_waitcnt lgkmcnt(0)
	s_branch .LBB0_530
